# v036 with the GEMM unit-start store drain relaxed from vmcnt(0) to vmcnt(4)
# speedup vs baseline: 1.0012x; 1.0012x over previous
; __device__ __forceinline__ int lane_id() { int l; asm volatile("v_mbcnt_lo_u32_b32 %0, -1, 0\n\tv_mbcnt_hi_u32_b32 %0, -1, %0" : "=v"(l)); return l; }
;     __device__ __forceinline__ bool next(int i, UnitG& u) const { if (!P.next(i, u)) return false; u.O = O + ((size_t)u.x0 * 256 * 2048 + (size_t)u.x1 * 256) * 2; u.ldo = 2048; u.kind = 0; return true; }
; template <class Epi, class Sched>
; __device__ __forceinline__ void gemm_phase(PG8_LAS unsigned char* lds, const Sched& S, const Epi& E, int tid_in) {
;     ...
;         int aoff, boff; { const int l3 = lane_id(), fr3 = l3 & 15, fq3 = l3 >> 4; aoff = lds_byte(wr * 64 + fr3, fq3 * 8); boff = lds_byte(wc * 32 + fr3, fq3 * 8); }
;         const bool has_next = S.next(ui + 1, nxt);
;         const char* nA = has_next ? nxt.A : cA; const char* nB = has_next ? nxt.B : cB;
;         const int nlda = has_next ? nxt.lda : cur.lda, nldb = has_next ? nxt.ldb : cur.ldb;
;         unsigned nvA, nvB; { int r2, c2; stage_rc((wid * 64 + lane_id()) * 16, r2, c2); const int rb2 = Epi::PERM ? ((r2 & ~31) + perm32(r2 & 31)) : r2;
;             nvA = (unsigned)(r2 * nlda + c2) * 2u; nvB = (unsigned)(rb2 * nldb + c2) * 2u; }
;         const unsigned nqA = (unsigned)nlda * 128u, nqB = (unsigned)nldb * 128u;
;         const int nt = cur.K / BK;
.LBB0_206:
	v_and_b32_e32 v1, 15, v0
	v_or_b32_e32 v2, s50, v1
	v_ashrrev_i32_e32 v3, 6, v0
	v_lshlrev_b32_e32 v4, 6, v2
	v_and_b32_e32 v5, 48, v0
	s_movk_i32 s57, 0x3c0
	v_lshlrev_b32_e32 v2, 2, v2
	v_and_or_b32 v4, v4, s57, v5
	v_lshl_add_u32 v6, v3, 10, s51
	v_and_b32_e32 v2, 32, v2
	v_lshlrev_b32_e32 v0, 2, v0
	s_waitcnt vmcnt(4)
	v_bitop3_b32 v32, v4, v6, v2 bitop3:0xde
	v_lshl_or_b32 v1, v1, 6, v5
	v_add_lshl_u32 v2, v3, s53, 10
	v_and_b32_e32 v0, 32, v0
	v_bitop3_b32 v137, v1, v2, v0 bitop3:0xde
	v_mbcnt_lo_u32_b32 v0, -1, 0
	v_mbcnt_hi_u32_b32 v0, -1, v0
	s_mov_b32 s57, 0xfffe0
	v_add_u32_e32 v0, s54, v0
	v_ashrrev_i32_e32 v2, 31, v0
	v_lshrrev_b32_e32 v2, 26, v2
	v_lshlrev_b32_e32 v1, 4, v0
	v_add_u32_e32 v2, v0, v2
	v_bfe_i32 v0, v0, 27, 1
	v_lshrrev_b32_e32 v0, 22, v0
	v_add_u32_e32 v0, v1, v0
	v_and_b32_e32 v0, 0xfffffc00, v0
	v_sub_u32_e32 v0, v1, v0
	v_lshrrev_b32_e32 v1, 4, v0
	v_bitop3_b32 v0, v1, v0, 32 bitop3:0x6c
	v_ashrrev_i32_e32 v3, 31, v0
	v_lshrrev_b32_e32 v3, 26, v3
	v_ashrrev_i32_e32 v2, 6, v2
	v_add_u32_e32 v3, v0, v3
	v_lshlrev_b32_e32 v1, 3, v2
	v_ashrrev_i32_e32 v4, 6, v3
	v_and_b32_e32 v3, 0xc0, v3
	v_and_b32_e32 v1, -16, v1
	v_sub_u32_e32 v0, v0, v3
	v_add_u32_e32 v1, v4, v1
	v_lshlrev_b32_e32 v2, 5, v2
	v_ashrrev_i16_sdwa v0, v205, sext(v0) dst_sel:DWORD dst_unused:UNUSED_PAD src0_sel:DWORD src1_sel:BYTE_0
	v_and_b32_e32 v2, 32, v2
	v_bfe_i32 v0, v0, 0, 16
	v_lshlrev_b32_e32 v3, 1, v1
	v_lshrrev_b32_e32 v5, 2, v1
	v_and_b32_e32 v4, 3, v4
	s_add_i32 s59, 0, 0x10000
	s_add_i32 s61, 0, 0x14000
	v_and_b32_e32 v3, 24, v3
	v_and_b32_e32 v5, 4, v5
	v_and_or_b32 v4, v1, s57, v4
	v_add_lshl_u32 v34, v2, v0, 1
	v_add_u32_e32 v134, s59, v137
	v_add_u32_e32 v135, s61, v137
	v_or3_b32 v33, v4, v5, v3
	v_lshl_add_u32 v128, v1, 12, v34
	ds_read_b128 v[0:3], v134
	ds_read_b128 v[4:7], v134 offset:1024
	ds_read_b128 v[8:11], v134 offset:2048
	ds_read_b128 v[12:15], v134 offset:3072
	ds_read_b128 v[16:19], v135
	ds_read_b128 v[20:23], v135 offset:1024
	ds_read_b128 v[24:27], v135 offset:2048
	ds_read_b128 v[28:31], v135 offset:3072
	v_lshl_add_u32 v129, v33, 12, v34
	v_mov_b32_e32 v133, v185
	v_lshl_add_u64 v[182:183], s[20:21], 0, v[132:133]
	s_add_i32 s57, s7, 0xc000
	v_add_u32_e32 v136, 0, v32
	v_lshl_add_u64 v[64:65], v[182:183], 0, s[80:81]
	s_mov_b32 m0, s57
	s_add_i32 s58, s7, 0xe000
	ds_read_b128 v[32:35], v136
	ds_read_b128 v[36:39], v136 offset:1024
	ds_read_b128 v[40:43], v136 offset:2048
	ds_read_b128 v[44:47], v136 offset:3072
	ds_read_b128 v[48:51], v136 offset:4096
	ds_read_b128 v[52:55], v136 offset:5120
	ds_read_b128 v[56:59], v136 offset:6144
	ds_read_b128 v[60:63], v136 offset:7168
	global_load_lds_dwordx4 v[64:65], off
	v_lshl_add_u64 v[64:65], v[182:183], 0, s[78:79]
	s_mov_b32 m0, s58
	s_nop 0
	global_load_lds_dwordx4 v[64:65], off
	s_waitcnt vmcnt(16)
	s_waitcnt lgkmcnt(0)
	s_barrier
	s_waitcnt lgkmcnt(0)
	v_mfma_f32_16x16x32_bf16 v[64:67], v[0:3], v[32:35], 0
	v_mfma_f32_16x16x32_bf16 v[68:71], v[8:11], v[32:35], 0
	v_mfma_f32_16x16x32_bf16 v[72:75], v[0:3], v[40:43], 0
	v_mfma_f32_16x16x32_bf16 v[76:79], v[8:11], v[40:43], 0
	v_mfma_f32_16x16x32_bf16 v[80:83], v[0:3], v[48:51], 0
	v_mfma_f32_16x16x32_bf16 v[84:87], v[8:11], v[48:51], 0
	v_mfma_f32_16x16x32_bf16 v[88:91], v[0:3], v[56:59], 0
	v_mfma_f32_16x16x32_bf16 v[92:95], v[8:11], v[56:59], 0
	v_mfma_f32_16x16x32_bf16 v[64:67], v[4:7], v[36:39], v[64:67]
	v_mfma_f32_16x16x32_bf16 v[68:71], v[12:15], v[36:39], v[68:71]
	v_mfma_f32_16x16x32_bf16 v[72:75], v[4:7], v[44:47], v[72:75]
	v_mfma_f32_16x16x32_bf16 v[76:79], v[12:15], v[44:47], v[76:79]
	v_mfma_f32_16x16x32_bf16 v[80:83], v[4:7], v[52:55], v[80:83]
	v_mfma_f32_16x16x32_bf16 v[84:87], v[12:15], v[52:55], v[84:87]
	v_mfma_f32_16x16x32_bf16 v[88:91], v[4:7], v[60:63], v[88:91]
	v_mfma_f32_16x16x32_bf16 v[100:103], v[12:15], v[60:63], v[92:95]
	v_mfma_f32_16x16x32_bf16 v[92:95], v[16:19], v[32:35], 0
	v_mfma_f32_16x16x32_bf16 v[32:35], v[24:27], v[32:35], 0
	v_mfma_f32_16x16x32_bf16 v[104:107], v[20:23], v[36:39], v[92:95]
	v_mfma_f32_16x16x32_bf16 v[32:35], v[28:31], v[36:39], v[32:35]
	v_mfma_f32_16x16x32_bf16 v[36:39], v[16:19], v[40:43], 0
	v_mfma_f32_16x16x32_bf16 v[40:43], v[24:27], v[40:43], 0
	v_mfma_f32_16x16x32_bf16 v[36:39], v[20:23], v[44:47], v[36:39]
	v_mfma_f32_16x16x32_bf16 v[40:43], v[28:31], v[44:47], v[40:43]
	v_mfma_f32_16x16x32_bf16 v[44:47], v[16:19], v[48:51], 0
	v_mfma_f32_16x16x32_bf16 v[48:51], v[24:27], v[48:51], 0
	v_mfma_f32_16x16x32_bf16 v[44:47], v[20:23], v[52:55], v[44:47]
	v_mfma_f32_16x16x32_bf16 v[48:51], v[28:31], v[52:55], v[48:51]
	v_mfma_f32_16x16x32_bf16 v[52:55], v[16:19], v[56:59], 0
	v_mfma_f32_16x16x32_bf16 v[56:59], v[24:27], v[56:59], 0
	v_mfma_f32_16x16x32_bf16 v[52:55], v[20:23], v[60:63], v[52:55]
	v_mfma_f32_16x16x32_bf16 v[56:59], v[28:31], v[60:63], v[56:59]
	s_barrier
	v_mov_b32_e32 v131, v185
	v_lshl_add_u64 v[248:249], s[22:23], 0, v[130:131]
	s_mov_b64 s[64:65], 0x100
	s_add_i32 s59, s59, s30
	v_lshl_add_u64 v[138:139], v[248:249], 0, s[64:65]
	s_mov_b32 m0, s59
	s_mov_b64 s[66:67], 0x40100
	s_add_i32 s60, s59, 0x2000
	ds_read_b128 v[60:63], v136 offset:16384
	ds_read_b128 v[92:95], v136 offset:17408
	ds_read_b128 v[96:99], v136 offset:18432
	ds_read_b128 v[108:111], v136 offset:19456
	ds_read_b128 v[112:115], v136 offset:20480
	ds_read_b128 v[116:119], v136 offset:21504
	ds_read_b128 v[120:123], v136 offset:22528
	ds_read_b128 v[124:127], v136 offset:23552
	global_load_lds_dwordx4 v[138:139], off
	v_lshl_add_u64 v[138:139], v[248:249], 0, s[66:67]
	s_mov_b32 m0, s60
	s_mov_b64 s[70:71], 0x80100
	s_add_i32 s61, s61, s30
	global_load_lds_dwordx4 v[138:139], off
	v_lshl_add_u64 v[138:139], v[248:249], 0, s[70:71]
	s_mov_b32 m0, s61
	s_mov_b64 s[72:73], 0xc0100
	s_add_i32 s62, s61, 0x2000
	global_load_lds_dwordx4 v[138:139], off
	v_lshl_add_u64 v[138:139], v[248:249], 0, s[72:73]
	s_mov_b32 m0, s62
	s_nop 0
	global_load_lds_dwordx4 v[138:139], off
	v_lshl_add_u64 v[138:139], v[182:183], 0, s[64:65]
	s_mov_b32 m0, s7
	s_nop 0
	global_load_lds_dwordx4 v[138:139], off
	v_lshl_add_u64 v[138:139], v[182:183], 0, s[66:67]
	s_mov_b32 m0, s31
	s_nop 0
	global_load_lds_dwordx4 v[138:139], off
	s_waitcnt vmcnt(16)
	s_waitcnt lgkmcnt(0)
	s_barrier
	s_waitcnt lgkmcnt(0)
	v_mfma_f32_16x16x32_bf16 v[138:141], v[0:3], v[60:63], 0
	v_mfma_f32_16x16x32_bf16 v[146:149], v[0:3], v[96:99], 0
	v_mfma_f32_16x16x32_bf16 v[154:157], v[0:3], v[112:115], 0
	v_mfma_f32_16x16x32_bf16 v[0:3], v[0:3], v[120:123], 0
	v_mfma_f32_16x16x32_bf16 v[138:141], v[4:7], v[92:95], v[138:141]
	v_mfma_f32_16x16x32_bf16 v[146:149], v[4:7], v[108:111], v[146:149]
	v_mfma_f32_16x16x32_bf16 v[154:157], v[4:7], v[116:119], v[154:157]
	v_mfma_f32_16x16x32_bf16 v[0:3], v[4:7], v[124:127], v[0:3]
	v_mfma_f32_16x16x32_bf16 v[4:7], v[8:11], v[120:123], 0
	v_mfma_f32_16x16x32_bf16 v[142:145], v[8:11], v[60:63], 0
	v_mfma_f32_16x16x32_bf16 v[150:153], v[8:11], v[96:99], 0
	v_mfma_f32_16x16x32_bf16 v[158:161], v[8:11], v[112:115], 0
	v_mfma_f32_16x16x32_bf16 v[4:7], v[12:15], v[124:127], v[4:7]
	v_mfma_f32_16x16x32_bf16 v[142:145], v[12:15], v[92:95], v[142:145]
	v_mfma_f32_16x16x32_bf16 v[150:153], v[12:15], v[108:111], v[150:153]
	v_mfma_f32_16x16x32_bf16 v[158:161], v[12:15], v[116:119], v[158:161]
	v_mfma_f32_16x16x32_bf16 v[12:15], v[24:27], v[60:63], 0
	v_mfma_f32_16x16x32_bf16 v[162:165], v[28:31], v[92:95], v[12:15]
	v_mfma_f32_16x16x32_bf16 v[12:15], v[16:19], v[96:99], 0
	v_mfma_f32_16x16x32_bf16 v[166:169], v[20:23], v[108:111], v[12:15]
	v_mfma_f32_16x16x32_bf16 v[12:15], v[24:27], v[96:99], 0
	v_mfma_f32_16x16x32_bf16 v[170:173], v[28:31], v[108:111], v[12:15]
	v_mfma_f32_16x16x32_bf16 v[12:15], v[16:19], v[112:115], 0
	v_mfma_f32_16x16x32_bf16 v[174:177], v[20:23], v[116:119], v[12:15]
	v_mfma_f32_16x16x32_bf16 v[12:15], v[24:27], v[112:115], 0
	v_mfma_f32_16x16x32_bf16 v[8:11], v[16:19], v[60:63], 0
	v_mfma_f32_16x16x32_bf16 v[178:181], v[28:31], v[116:119], v[12:15]
	v_mfma_f32_16x16x32_bf16 v[12:15], v[16:19], v[120:123], 0
	v_mfma_f32_16x16x32_bf16 v[8:11], v[20:23], v[92:95], v[8:11]
	v_mfma_f32_16x16x32_bf16 v[188:191], v[20:23], v[124:127], v[12:15]
	v_mfma_f32_16x16x32_bf16 v[12:15], v[24:27], v[120:123], 0
	v_mfma_f32_16x16x32_bf16 v[192:195], v[28:31], v[124:127], v[12:15]
	s_barrier
	s_add_i32 s63, 0, 0x18000
	s_add_i32 s65, 0, 0x1c000
	v_add_u32_e32 v131, s63, v137
	v_add_u32_e32 v137, s65, v137
	s_nop 0
	ds_read_b128 v[12:15], v131
	ds_read_b128 v[20:23], v131 offset:1024
	ds_read_b128 v[24:27], v131 offset:2048
	ds_read_b128 v[196:199], v131 offset:3072
	ds_read_b128 v[200:203], v137
	ds_read_b128 v[212:215], v137 offset:1024
	ds_read_b128 v[216:219], v137 offset:2048
	ds_read_b128 v[220:223], v137 offset:3072
	s_mov_b32 m0, s34
	v_lshl_add_u64 v[92:93], v[182:183], 0, s[70:71]
	ds_read_b128 v[16:19], v136 offset:32768
	ds_read_b128 v[28:31], v136 offset:33792
	ds_read_b128 v[60:63], v136 offset:34816
	ds_read_b128 v[224:227], v136 offset:35840
	ds_read_b128 v[228:231], v136 offset:36864
	ds_read_b128 v[232:235], v136 offset:37888
	ds_read_b128 v[236:239], v136 offset:38912
	ds_read_b128 v[240:243], v136 offset:39936
	global_load_lds_dwordx4 v[92:93], off
	v_lshl_add_u64 v[92:93], v[182:183], 0, s[72:73]
	s_mov_b32 m0, s35
	s_nop 0
	global_load_lds_dwordx4 v[92:93], off
	s_waitcnt vmcnt(8)
	s_waitcnt lgkmcnt(0)
	s_barrier
	s_waitcnt lgkmcnt(0)
	v_mfma_f32_16x16x32_bf16 v[64:67], v[12:15], v[16:19], v[64:67]
	v_mfma_f32_16x16x32_bf16 v[124:127], v[20:23], v[28:31], v[64:67]
	v_mfma_f32_16x16x32_bf16 v[64:67], v[24:27], v[16:19], v[68:71]
	v_mfma_f32_16x16x32_bf16 v[112:115], v[196:199], v[28:31], v[64:67]
	v_mfma_f32_16x16x32_bf16 v[64:67], v[12:15], v[60:63], v[72:75]
	v_mfma_f32_16x16x32_bf16 v[108:111], v[20:23], v[224:227], v[64:67]
	v_mfma_f32_16x16x32_bf16 v[64:67], v[24:27], v[60:63], v[76:79]
	v_mfma_f32_16x16x32_bf16 v[96:99], v[196:199], v[224:227], v[64:67]
	v_mfma_f32_16x16x32_bf16 v[64:67], v[12:15], v[228:231], v[80:83]
	v_mfma_f32_16x16x32_bf16 v[92:95], v[20:23], v[232:235], v[64:67]
	v_mfma_f32_16x16x32_bf16 v[64:67], v[24:27], v[228:231], v[84:87]
	v_mfma_f32_16x16x32_bf16 v[80:83], v[196:199], v[232:235], v[64:67]
	v_mfma_f32_16x16x32_bf16 v[64:67], v[12:15], v[236:239], v[88:91]
	v_mfma_f32_16x16x32_bf16 v[76:79], v[20:23], v[240:243], v[64:67]
	v_mfma_f32_16x16x32_bf16 v[64:67], v[24:27], v[236:239], v[100:103]
	v_mfma_f32_16x16x32_bf16 v[64:67], v[196:199], v[240:243], v[64:67]
	v_mfma_f32_16x16x32_bf16 v[68:71], v[200:203], v[16:19], v[104:107]
	v_mfma_f32_16x16x32_bf16 v[16:19], v[216:219], v[16:19], v[32:35]
	v_mfma_f32_16x16x32_bf16 v[116:119], v[220:223], v[28:31], v[16:19]
	v_mfma_f32_16x16x32_bf16 v[16:19], v[200:203], v[60:63], v[36:39]
	v_mfma_f32_16x16x32_bf16 v[104:107], v[212:215], v[224:227], v[16:19]
	v_mfma_f32_16x16x32_bf16 v[16:19], v[216:219], v[60:63], v[40:43]
	v_mfma_f32_16x16x32_bf16 v[100:103], v[220:223], v[224:227], v[16:19]
	v_mfma_f32_16x16x32_bf16 v[16:19], v[200:203], v[228:231], v[44:47]
	v_mfma_f32_16x16x32_bf16 v[88:91], v[212:215], v[232:235], v[16:19]
	v_mfma_f32_16x16x32_bf16 v[16:19], v[216:219], v[228:231], v[48:51]
	v_mfma_f32_16x16x32_bf16 v[84:87], v[220:223], v[232:235], v[16:19]
	v_mfma_f32_16x16x32_bf16 v[16:19], v[200:203], v[236:239], v[52:55]
	v_mfma_f32_16x16x32_bf16 v[72:75], v[212:215], v[240:243], v[16:19]
	v_mfma_f32_16x16x32_bf16 v[16:19], v[216:219], v[236:239], v[56:59]
	v_mfma_f32_16x16x32_bf16 v[120:123], v[212:215], v[28:31], v[68:71]
	v_mfma_f32_16x16x32_bf16 v[68:71], v[220:223], v[240:243], v[16:19]
	s_barrier
; #define PG8_WAIT_VP() asm volatile("s_waitcnt vmcnt(%0)" :: "n"(8 + Epi::NST) : "memory")
; template <class Epi, class Sched>
; __device__ __forceinline__ void gemm_phase(PG8_LAS unsigned char* lds, const Sched& S, const Epi& E, int tid_in) {
;     ...
;         { const int t = 0; PG8_KITER(PG8_WAIT_VP()); }
	s_mov_b64 s[70:71], 0x180
	s_add_i32 s63, s63, s30
	s_nop 1
	v_lshl_add_u64 v[16:17], v[248:249], 0, s[70:71]
	s_mov_b32 m0, s63
	s_mov_b64 s[72:73], 0x40180
	s_add_i32 s64, s63, 0x2000
	ds_read_b128 v[36:39], v136 offset:49152
	ds_read_b128 v[40:43], v136 offset:50176
	ds_read_b128 v[224:227], v136 offset:51200
	ds_read_b128 v[228:231], v136 offset:52224
	ds_read_b128 v[232:235], v136 offset:53248
	ds_read_b128 v[236:239], v136 offset:54272
	ds_read_b128 v[240:243], v136 offset:55296
	ds_read_b128 v[244:247], v136 offset:56320
	global_load_lds_dwordx4 v[16:17], off
	v_lshl_add_u64 v[16:17], v[248:249], 0, s[72:73]
	s_mov_b32 m0, s64
	s_add_i32 s65, s65, s30
	global_load_lds_dwordx4 v[16:17], off
	v_lshl_add_u64 v[16:17], v[248:249], 0, s[92:93]
	s_mov_b32 m0, s65
	s_add_i32 s66, s65, 0x2000
	global_load_lds_dwordx4 v[16:17], off
	v_lshl_add_u64 v[16:17], v[248:249], 0, vcc
	s_mov_b32 m0, s66
	s_nop 0
	global_load_lds_dwordx4 v[16:17], off
	v_lshl_add_u64 v[16:17], v[182:183], 0, s[70:71]
	s_mov_b32 m0, s48
	s_nop 0
	global_load_lds_dwordx4 v[16:17], off
	v_lshl_add_u64 v[16:17], v[182:183], 0, s[72:73]
	s_mov_b32 m0, s49
	s_nop 0
	global_load_lds_dwordx4 v[16:17], off
	s_waitcnt vmcnt(8)
	s_waitcnt lgkmcnt(0)
	s_barrier
	s_waitcnt lgkmcnt(0)
	v_mfma_f32_16x16x32_bf16 v[16:19], v[12:15], v[36:39], v[138:141]
	v_mfma_f32_16x16x32_bf16 v[60:63], v[20:23], v[40:43], v[16:19]
	v_mfma_f32_16x16x32_bf16 v[16:19], v[24:27], v[36:39], v[142:145]
	v_mfma_f32_16x16x32_bf16 v[48:51], v[196:199], v[40:43], v[16:19]
	v_mfma_f32_16x16x32_bf16 v[16:19], v[12:15], v[224:227], v[146:149]
	v_mfma_f32_16x16x32_bf16 v[44:47], v[20:23], v[228:231], v[16:19]
	v_mfma_f32_16x16x32_bf16 v[16:19], v[24:27], v[224:227], v[150:153]
	v_mfma_f32_16x16x32_bf16 v[32:35], v[196:199], v[228:231], v[16:19]
	v_mfma_f32_16x16x32_bf16 v[16:19], v[12:15], v[232:235], v[154:157]
	v_mfma_f32_16x16x32_bf16 v[0:3], v[12:15], v[240:243], v[0:3]
	v_mfma_f32_16x16x32_bf16 v[28:31], v[20:23], v[236:239], v[16:19]
	v_mfma_f32_16x16x32_bf16 v[16:19], v[24:27], v[232:235], v[158:161]
	v_mfma_f32_16x16x32_bf16 v[12:15], v[20:23], v[244:247], v[0:3]
	v_mfma_f32_16x16x32_bf16 v[0:3], v[24:27], v[240:243], v[4:7]
	v_mfma_f32_16x16x32_bf16 v[16:19], v[196:199], v[236:239], v[16:19]
	v_mfma_f32_16x16x32_bf16 v[0:3], v[196:199], v[244:247], v[0:3]
	v_mfma_f32_16x16x32_bf16 v[4:7], v[200:203], v[36:39], v[8:11]
	v_mfma_f32_16x16x32_bf16 v[56:59], v[212:215], v[40:43], v[4:7]
	v_mfma_f32_16x16x32_bf16 v[4:7], v[216:219], v[36:39], v[162:165]
	v_mfma_f32_16x16x32_bf16 v[52:55], v[220:223], v[40:43], v[4:7]
	v_mfma_f32_16x16x32_bf16 v[4:7], v[200:203], v[224:227], v[166:169]
	v_mfma_f32_16x16x32_bf16 v[40:43], v[212:215], v[228:231], v[4:7]
	v_mfma_f32_16x16x32_bf16 v[4:7], v[216:219], v[224:227], v[170:173]
	v_mfma_f32_16x16x32_bf16 v[36:39], v[220:223], v[228:231], v[4:7]
	v_mfma_f32_16x16x32_bf16 v[4:7], v[200:203], v[232:235], v[174:177]
	v_mfma_f32_16x16x32_bf16 v[24:27], v[212:215], v[236:239], v[4:7]
	v_mfma_f32_16x16x32_bf16 v[4:7], v[216:219], v[232:235], v[178:181]
	v_mfma_f32_16x16x32_bf16 v[20:23], v[220:223], v[236:239], v[4:7]
	v_mfma_f32_16x16x32_bf16 v[4:7], v[200:203], v[240:243], v[188:191]
	v_mfma_f32_16x16x32_bf16 v[8:11], v[212:215], v[244:247], v[4:7]
	v_mfma_f32_16x16x32_bf16 v[4:7], v[216:219], v[240:243], v[192:195]
	v_mfma_f32_16x16x32_bf16 v[4:7], v[220:223], v[244:247], v[4:7]
	s_barrier
	s_add_u32 s20, s20, 0x80180
	s_addc_u32 s21, s21, 0
	s_add_u32 s67, s22, 0x200
	s_addc_u32 s68, s23, 0
	s_mov_b32 s70, 0

; __device__ __forceinline__ int lane_id() { int l; asm volatile("v_mbcnt_lo_u32_b32 %0, -1, 0\n\tv_mbcnt_hi_u32_b32 %0, -1, %0" : "=v"(l)); return l; }
;     __device__ __forceinline__ bool next(int i, UnitG& u) const { if (!P.next(i, u)) return false; u.O = O + ((size_t)u.x0 * 256 * 2048 + (size_t)u.x1 * 256) * 2; u.ldo = 2048; u.kind = 0; return true; }
; template <class Epi, class Sched>
; __device__ __forceinline__ void gemm_phase(PG8_LAS unsigned char* lds, const Sched& S, const Epi& E, int tid_in) {
;     ...
;         int aoff, boff; { const int l3 = lane_id(), fr3 = l3 & 15, fq3 = l3 >> 4; aoff = lds_byte(wr * 64 + fr3, fq3 * 8); boff = lds_byte(wc * 32 + fr3, fq3 * 8); }
;         const bool has_next = S.next(ui + 1, nxt);
;         const char* nA = has_next ? nxt.A : cA; const char* nB = has_next ? nxt.B : cB;
;         const int nlda = has_next ? nxt.lda : cur.lda, nldb = has_next ? nxt.ldb : cur.ldb;
;         unsigned nvA, nvB; { int r2, c2; stage_rc((wid * 64 + lane_id()) * 16, r2, c2); const int rb2 = Epi::PERM ? ((r2 & ~31) + perm32(r2 & 31)) : r2;
;             nvA = (unsigned)(r2 * nlda + c2) * 2u; nvB = (unsigned)(rb2 * nldb + c2) * 2u; }
;         const unsigned nqA = (unsigned)nlda * 128u, nqB = (unsigned)nldb * 128u;
;         const int nt = cur.K / BK;
.LBB0_273:
	v_and_b32_e32 v1, 15, v0
	v_or_b32_e32 v2, s50, v1
	v_ashrrev_i32_e32 v3, 6, v0
	v_lshlrev_b32_e32 v4, 6, v2
	v_and_b32_e32 v5, 48, v0
	s_movk_i32 s57, 0x3c0
	v_lshlrev_b32_e32 v2, 2, v2
	v_and_or_b32 v4, v4, s57, v5
	v_lshl_add_u32 v6, v3, 10, s51
	v_and_b32_e32 v2, 32, v2
	v_lshlrev_b32_e32 v0, 2, v0
	s_waitcnt vmcnt(4)
	v_bitop3_b32 v32, v4, v6, v2 bitop3:0xde
	v_lshl_or_b32 v1, v1, 6, v5
	v_add_lshl_u32 v2, v3, s53, 10
	v_and_b32_e32 v0, 32, v0
	v_bitop3_b32 v119, v1, v2, v0 bitop3:0xde
	v_mbcnt_lo_u32_b32 v0, -1, 0
	v_mbcnt_hi_u32_b32 v0, -1, v0
	s_mov_b32 s57, 0x7fffe0
	v_add_u32_e32 v0, s54, v0
	v_ashrrev_i32_e32 v2, 31, v0
	v_lshrrev_b32_e32 v2, 26, v2
	v_lshlrev_b32_e32 v1, 4, v0
	v_add_u32_e32 v2, v0, v2
	v_bfe_i32 v0, v0, 27, 1
	v_lshrrev_b32_e32 v0, 22, v0
	v_add_u32_e32 v0, v1, v0
	v_and_b32_e32 v0, 0xfffffc00, v0
	v_sub_u32_e32 v0, v1, v0
	v_lshrrev_b32_e32 v1, 4, v0
	v_bitop3_b32 v0, v1, v0, 32 bitop3:0x6c
	v_ashrrev_i32_e32 v3, 31, v0
	v_ashrrev_i32_e32 v2, 6, v2
	v_lshrrev_b32_e32 v3, 26, v3
	v_lshlrev_b32_e32 v1, 3, v2
	v_add_u32_e32 v3, v0, v3
	v_and_b32_e32 v1, -16, v1
	v_ashrrev_i32_e32 v4, 6, v3
	v_add_u32_e32 v33, v4, v1
	v_lshlrev_b32_e32 v1, 5, v2
	v_and_b32_e32 v2, 0xc0, v3
	v_sub_u32_e32 v0, v0, v2
	v_and_b32_e32 v1, 32, v1
	v_ashrrev_i16_sdwa v0, v205, sext(v0) dst_sel:DWORD dst_unused:UNUSED_PAD src0_sel:DWORD src1_sel:BYTE_0
	v_add_u32_sdwa v34, v1, sext(v0) dst_sel:DWORD dst_unused:UNUSED_PAD src0_sel:DWORD src1_sel:WORD_0
	v_lshlrev_b32_e32 v0, 1, v33
	v_lshrrev_b32_e32 v1, 2, v33
	v_and_b32_e32 v2, 3, v4
	s_add_i32 s59, 0, 0x10000
	s_add_i32 s61, 0, 0x14000
	v_and_b32_e32 v0, 24, v0
	v_and_b32_e32 v1, 4, v1
	v_and_or_b32 v2, v33, s57, v2
	v_add_u32_e32 v116, s59, v119
	v_add_u32_e32 v117, s61, v119
	v_or3_b32 v35, v2, v1, v0
	ds_read_b128 v[0:3], v116
	ds_read_b128 v[4:7], v116 offset:1024
	ds_read_b128 v[8:11], v116 offset:2048
	ds_read_b128 v[12:15], v116 offset:3072
	ds_read_b128 v[16:19], v117
	ds_read_b128 v[20:23], v117 offset:1024
	ds_read_b128 v[24:27], v117 offset:2048
	ds_read_b128 v[28:31], v117 offset:3072
	s_movk_i32 s57, 0x1600
	v_mul_lo_u32 v33, v33, s57
	v_add_lshl_u32 v186, v34, v33, 1
	v_mul_u32_u24_e32 v33, 0x1600, v35
	v_add_lshl_u32 v211, v33, v34, 1
	v_mov_b32_e32 v115, v185
	v_lshl_add_u64 v[244:245], s[20:21], 0, v[114:115]
	s_add_i32 s57, s31, 0xc000
	v_add_u32_e32 v118, 0, v32
	v_lshl_add_u64 v[64:65], v[244:245], 0, s[40:41]
	s_mov_b32 m0, s57
	s_add_i32 s58, s31, 0xe000
	ds_read_b128 v[32:35], v118
	ds_read_b128 v[36:39], v118 offset:1024
	ds_read_b128 v[40:43], v118 offset:2048
	ds_read_b128 v[44:47], v118 offset:3072
	ds_read_b128 v[48:51], v118 offset:4096
	ds_read_b128 v[52:55], v118 offset:5120
	ds_read_b128 v[56:59], v118 offset:6144
	ds_read_b128 v[60:63], v118 offset:7168
	global_load_lds_dwordx4 v[64:65], off
	v_lshl_add_u64 v[64:65], v[244:245], 0, s[42:43]
	s_mov_b32 m0, s58
	s_nop 0
	global_load_lds_dwordx4 v[64:65], off
	s_waitcnt vmcnt(24)
	s_waitcnt lgkmcnt(0)
	s_barrier
	s_waitcnt lgkmcnt(0)
	v_mfma_f32_16x16x32_bf16 v[88:91], v[0:3], v[56:59], 0
	v_mfma_f32_16x16x32_bf16 v[64:67], v[0:3], v[32:35], 0
	v_mfma_f32_16x16x32_bf16 v[68:71], v[8:11], v[32:35], 0
	v_mfma_f32_16x16x32_bf16 v[72:75], v[0:3], v[40:43], 0
	v_mfma_f32_16x16x32_bf16 v[76:79], v[8:11], v[40:43], 0
	v_mfma_f32_16x16x32_bf16 v[80:83], v[0:3], v[48:51], 0
	v_mfma_f32_16x16x32_bf16 v[84:87], v[8:11], v[48:51], 0
	v_mfma_f32_16x16x32_bf16 v[96:99], v[4:7], v[60:63], v[88:91]
	v_mfma_f32_16x16x32_bf16 v[88:91], v[8:11], v[56:59], 0
	v_mfma_f32_16x16x32_bf16 v[64:67], v[4:7], v[36:39], v[64:67]
	v_mfma_f32_16x16x32_bf16 v[68:71], v[12:15], v[36:39], v[68:71]
	v_mfma_f32_16x16x32_bf16 v[72:75], v[4:7], v[44:47], v[72:75]
	v_mfma_f32_16x16x32_bf16 v[76:79], v[12:15], v[44:47], v[76:79]
	v_mfma_f32_16x16x32_bf16 v[80:83], v[4:7], v[52:55], v[80:83]
	v_mfma_f32_16x16x32_bf16 v[84:87], v[12:15], v[52:55], v[84:87]
	v_mfma_f32_16x16x32_bf16 v[100:103], v[12:15], v[60:63], v[88:91]
	v_mfma_f32_16x16x32_bf16 v[88:91], v[16:19], v[32:35], 0
	v_mfma_f32_16x16x32_bf16 v[32:35], v[24:27], v[32:35], 0
	v_mfma_f32_16x16x32_bf16 v[120:123], v[20:23], v[36:39], v[88:91]
	v_mfma_f32_16x16x32_bf16 v[32:35], v[28:31], v[36:39], v[32:35]
	v_mfma_f32_16x16x32_bf16 v[36:39], v[16:19], v[40:43], 0
	v_mfma_f32_16x16x32_bf16 v[40:43], v[24:27], v[40:43], 0
	v_mfma_f32_16x16x32_bf16 v[36:39], v[20:23], v[44:47], v[36:39]
	v_mfma_f32_16x16x32_bf16 v[40:43], v[28:31], v[44:47], v[40:43]
	v_mfma_f32_16x16x32_bf16 v[44:47], v[16:19], v[48:51], 0
	v_mfma_f32_16x16x32_bf16 v[48:51], v[24:27], v[48:51], 0
	v_mfma_f32_16x16x32_bf16 v[44:47], v[20:23], v[52:55], v[44:47]
	v_mfma_f32_16x16x32_bf16 v[48:51], v[28:31], v[52:55], v[48:51]
	v_mfma_f32_16x16x32_bf16 v[52:55], v[16:19], v[56:59], 0
	v_mfma_f32_16x16x32_bf16 v[56:59], v[24:27], v[56:59], 0
	v_mfma_f32_16x16x32_bf16 v[52:55], v[20:23], v[60:63], v[52:55]
	v_mfma_f32_16x16x32_bf16 v[56:59], v[28:31], v[60:63], v[56:59]
	s_barrier
	v_mov_b32_e32 v113, v185
	v_lshl_add_u64 v[246:247], s[22:23], 0, v[112:113]
	s_mov_b64 s[64:65], 0x100
	s_add_i32 s59, s59, s30
	v_lshl_add_u64 v[136:137], v[246:247], 0, s[64:65]
	s_mov_b32 m0, s59
	s_mov_b64 s[66:67], 0xb0100
	s_add_i32 s60, s59, 0x2000
	ds_read_b128 v[60:63], v118 offset:16384
	ds_read_b128 v[88:91], v118 offset:17408
	ds_read_b128 v[92:95], v118 offset:18432
	ds_read_b128 v[104:107], v118 offset:19456
	ds_read_b128 v[108:111], v118 offset:20480
	ds_read_b128 v[124:127], v118 offset:21504
	ds_read_b128 v[128:131], v118 offset:22528
	ds_read_b128 v[132:135], v118 offset:23552
	global_load_lds_dwordx4 v[136:137], off
	v_lshl_add_u64 v[136:137], v[246:247], 0, s[66:67]
	s_mov_b32 m0, s60
	s_mov_b64 s[70:71], 0x160100
	s_add_i32 s61, s61, s30
	global_load_lds_dwordx4 v[136:137], off
	v_lshl_add_u64 v[136:137], v[246:247], 0, s[70:71]
	s_mov_b32 m0, s61
	s_mov_b64 s[72:73], 0x210100
	s_add_i32 s62, s61, 0x2000
	global_load_lds_dwordx4 v[136:137], off
	v_lshl_add_u64 v[136:137], v[246:247], 0, s[72:73]
	s_mov_b32 m0, s62
	s_nop 0
	global_load_lds_dwordx4 v[136:137], off
	v_lshl_add_u64 v[136:137], v[244:245], 0, s[64:65]
	s_mov_b32 m0, s31
	s_nop 0
	global_load_lds_dwordx4 v[136:137], off
	v_lshl_add_u64 v[136:137], v[244:245], 0, s[66:67]
	s_mov_b32 m0, s35
	s_nop 0
	global_load_lds_dwordx4 v[136:137], off
	s_waitcnt vmcnt(24)
	s_waitcnt lgkmcnt(0)
	s_barrier
	s_waitcnt lgkmcnt(0)
	v_mfma_f32_16x16x32_bf16 v[136:139], v[0:3], v[60:63], 0
	v_mfma_f32_16x16x32_bf16 v[144:147], v[0:3], v[92:95], 0
	v_mfma_f32_16x16x32_bf16 v[152:155], v[0:3], v[108:111], 0
	v_mfma_f32_16x16x32_bf16 v[0:3], v[0:3], v[128:131], 0
	v_mfma_f32_16x16x32_bf16 v[136:139], v[4:7], v[88:91], v[136:139]
	v_mfma_f32_16x16x32_bf16 v[144:147], v[4:7], v[104:107], v[144:147]
	v_mfma_f32_16x16x32_bf16 v[152:155], v[4:7], v[124:127], v[152:155]
	v_mfma_f32_16x16x32_bf16 v[0:3], v[4:7], v[132:135], v[0:3]
	v_mfma_f32_16x16x32_bf16 v[4:7], v[8:11], v[128:131], 0
	v_mfma_f32_16x16x32_bf16 v[140:143], v[8:11], v[60:63], 0
	v_mfma_f32_16x16x32_bf16 v[148:151], v[8:11], v[92:95], 0
	v_mfma_f32_16x16x32_bf16 v[156:159], v[8:11], v[108:111], 0
	v_mfma_f32_16x16x32_bf16 v[4:7], v[12:15], v[132:135], v[4:7]
	v_mfma_f32_16x16x32_bf16 v[140:143], v[12:15], v[88:91], v[140:143]
	v_mfma_f32_16x16x32_bf16 v[148:151], v[12:15], v[104:107], v[148:151]
	v_mfma_f32_16x16x32_bf16 v[156:159], v[12:15], v[124:127], v[156:159]
	v_mfma_f32_16x16x32_bf16 v[8:11], v[16:19], v[60:63], 0
	v_mfma_f32_16x16x32_bf16 v[160:163], v[20:23], v[88:91], v[8:11]
	v_mfma_f32_16x16x32_bf16 v[8:11], v[24:27], v[60:63], 0
	v_mfma_f32_16x16x32_bf16 v[180:183], v[28:31], v[88:91], v[8:11]
	v_mfma_f32_16x16x32_bf16 v[8:11], v[16:19], v[92:95], 0
	v_mfma_f32_16x16x32_bf16 v[188:191], v[20:23], v[104:107], v[8:11]
	v_mfma_f32_16x16x32_bf16 v[8:11], v[24:27], v[92:95], 0
	v_mfma_f32_16x16x32_bf16 v[192:195], v[28:31], v[104:107], v[8:11]
	v_mfma_f32_16x16x32_bf16 v[8:11], v[16:19], v[108:111], 0
	v_mfma_f32_16x16x32_bf16 v[196:199], v[20:23], v[124:127], v[8:11]
	v_mfma_f32_16x16x32_bf16 v[8:11], v[24:27], v[108:111], 0
	v_mfma_f32_16x16x32_bf16 v[124:127], v[28:31], v[124:127], v[8:11]
	v_mfma_f32_16x16x32_bf16 v[8:11], v[16:19], v[128:131], 0
	v_mfma_f32_16x16x32_bf16 v[200:203], v[20:23], v[132:135], v[8:11]
	v_mfma_f32_16x16x32_bf16 v[8:11], v[24:27], v[128:131], 0
	v_mfma_f32_16x16x32_bf16 v[128:131], v[28:31], v[132:135], v[8:11]
	s_barrier
	s_add_i32 s63, 0, 0x18000
	s_add_i32 s65, 0, 0x1c000
	v_add_u32_e32 v113, s63, v119
	v_add_u32_e32 v119, s65, v119
	s_nop 0
	ds_read_b128 v[8:11], v113
	ds_read_b128 v[12:15], v113 offset:1024
	ds_read_b128 v[16:19], v113 offset:2048
	ds_read_b128 v[20:23], v113 offset:3072
	ds_read_b128 v[132:135], v119
	ds_read_b128 v[212:215], v119 offset:1024
	ds_read_b128 v[216:219], v119 offset:2048
	ds_read_b128 v[220:223], v119 offset:3072
	s_mov_b32 m0, s48
	v_lshl_add_u64 v[88:89], v[244:245], 0, s[70:71]
	ds_read_b128 v[24:27], v118 offset:32768
	ds_read_b128 v[28:31], v118 offset:33792
	ds_read_b128 v[60:63], v118 offset:34816
	ds_read_b128 v[224:227], v118 offset:35840
	ds_read_b128 v[228:231], v118 offset:36864
	ds_read_b128 v[232:235], v118 offset:37888
	ds_read_b128 v[236:239], v118 offset:38912
	ds_read_b128 v[240:243], v118 offset:39936
	global_load_lds_dwordx4 v[88:89], off
	v_lshl_add_u64 v[88:89], v[244:245], 0, s[72:73]
	s_mov_b32 m0, s49
	s_nop 0
	global_load_lds_dwordx4 v[88:89], off
	s_waitcnt vmcnt(8)
	s_waitcnt lgkmcnt(0)
	s_barrier
; #define PG8_WAIT_VP() asm volatile("s_waitcnt vmcnt(%0)" :: "n"(8 + Epi::NST) : "memory")
; template <class Epi, class Sched>
; __device__ __forceinline__ void gemm_phase(PG8_LAS unsigned char* lds, const Sched& S, const Epi& E, int tid_in) {
;     ...
;         { const int t = 0; PG8_KITER(PG8_WAIT_VP()); }
	s_waitcnt lgkmcnt(0)
	v_mfma_f32_16x16x32_bf16 v[64:67], v[8:11], v[24:27], v[64:67]
	v_mfma_f32_16x16x32_bf16 v[172:175], v[12:15], v[28:31], v[64:67]
	v_mfma_f32_16x16x32_bf16 v[64:67], v[16:19], v[24:27], v[68:71]
	v_mfma_f32_16x16x32_bf16 v[164:167], v[20:23], v[28:31], v[64:67]
	v_mfma_f32_16x16x32_bf16 v[64:67], v[8:11], v[60:63], v[72:75]
	v_mfma_f32_16x16x32_bf16 v[108:111], v[12:15], v[224:227], v[64:67]
	v_mfma_f32_16x16x32_bf16 v[64:67], v[16:19], v[60:63], v[76:79]
	v_mfma_f32_16x16x32_bf16 v[104:107], v[20:23], v[224:227], v[64:67]
	v_mfma_f32_16x16x32_bf16 v[64:67], v[8:11], v[228:231], v[80:83]
	v_mfma_f32_16x16x32_bf16 v[92:95], v[12:15], v[232:235], v[64:67]
	v_mfma_f32_16x16x32_bf16 v[64:67], v[16:19], v[228:231], v[84:87]
	v_mfma_f32_16x16x32_bf16 v[88:91], v[20:23], v[232:235], v[64:67]
	v_mfma_f32_16x16x32_bf16 v[64:67], v[8:11], v[236:239], v[96:99]
	v_mfma_f32_16x16x32_bf16 v[76:79], v[12:15], v[240:243], v[64:67]
	v_mfma_f32_16x16x32_bf16 v[64:67], v[16:19], v[236:239], v[100:103]
	v_mfma_f32_16x16x32_bf16 v[68:71], v[20:23], v[240:243], v[64:67]
	v_mfma_f32_16x16x32_bf16 v[64:67], v[132:135], v[24:27], v[120:123]
	v_mfma_f32_16x16x32_bf16 v[24:27], v[216:219], v[24:27], v[32:35]
	v_mfma_f32_16x16x32_bf16 v[168:171], v[220:223], v[28:31], v[24:27]
	v_mfma_f32_16x16x32_bf16 v[24:27], v[132:135], v[60:63], v[36:39]
	v_mfma_f32_16x16x32_bf16 v[100:103], v[212:215], v[224:227], v[24:27]
	v_mfma_f32_16x16x32_bf16 v[24:27], v[216:219], v[60:63], v[40:43]
	v_mfma_f32_16x16x32_bf16 v[96:99], v[220:223], v[224:227], v[24:27]
	v_mfma_f32_16x16x32_bf16 v[24:27], v[132:135], v[228:231], v[44:47]
	v_mfma_f32_16x16x32_bf16 v[84:87], v[212:215], v[232:235], v[24:27]
	v_mfma_f32_16x16x32_bf16 v[24:27], v[216:219], v[228:231], v[48:51]
	v_mfma_f32_16x16x32_bf16 v[80:83], v[220:223], v[232:235], v[24:27]
	v_mfma_f32_16x16x32_bf16 v[24:27], v[132:135], v[236:239], v[52:55]
	v_mfma_f32_16x16x32_bf16 v[176:179], v[212:215], v[28:31], v[64:67]
	v_mfma_f32_16x16x32_bf16 v[64:67], v[212:215], v[240:243], v[24:27]
	v_mfma_f32_16x16x32_bf16 v[24:27], v[216:219], v[236:239], v[56:59]
	v_mfma_f32_16x16x32_bf16 v[52:55], v[220:223], v[240:243], v[24:27]
	s_barrier
	s_mov_b64 s[70:71], 0x180
	s_add_i32 s63, s63, s30
	s_nop 2
	v_lshl_add_u64 v[24:25], v[246:247], 0, s[70:71]
	s_mov_b32 m0, s63
	s_mov_b64 s[72:73], 0xb0180
	s_add_i32 s64, s63, 0x2000
	ds_read_b128 v[32:35], v118 offset:49152
	ds_read_b128 v[36:39], v118 offset:50176
	ds_read_b128 v[120:123], v118 offset:51200
	ds_read_b128 v[224:227], v118 offset:52224
	ds_read_b128 v[228:231], v118 offset:53248
	ds_read_b128 v[232:235], v118 offset:54272
	ds_read_b128 v[236:239], v118 offset:55296
	ds_read_b128 v[240:243], v118 offset:56320
	global_load_lds_dwordx4 v[24:25], off
	v_lshl_add_u64 v[24:25], v[246:247], 0, s[72:73]
	s_mov_b32 m0, s64
	s_mov_b64 s[66:67], 0x160180
	s_add_i32 s65, s65, s30
	global_load_lds_dwordx4 v[24:25], off
	v_lshl_add_u64 v[24:25], v[246:247], 0, s[66:67]
	s_mov_b32 m0, s65
	s_mov_b64 s[66:67], 0x210180
	global_load_lds_dwordx4 v[24:25], off
	v_lshl_add_u64 v[24:25], v[246:247], 0, s[66:67]
	s_add_i32 s66, s65, 0x2000
	s_mov_b32 m0, s66
	s_nop 0
	global_load_lds_dwordx4 v[24:25], off
	v_lshl_add_u64 v[24:25], v[244:245], 0, s[70:71]
	s_mov_b32 m0, s46
	s_nop 0
	global_load_lds_dwordx4 v[24:25], off
	v_lshl_add_u64 v[24:25], v[244:245], 0, s[72:73]
	s_mov_b32 m0, s47
	s_nop 0
	global_load_lds_dwordx4 v[24:25], off
	s_waitcnt vmcnt(8)
	s_waitcnt lgkmcnt(0)
	s_barrier
	s_waitcnt lgkmcnt(0)
	v_mfma_f32_16x16x32_bf16 v[24:27], v[8:11], v[32:35], v[136:139]
	v_mfma_f32_16x16x32_bf16 v[72:75], v[12:15], v[36:39], v[24:27]
	v_mfma_f32_16x16x32_bf16 v[24:27], v[16:19], v[32:35], v[140:143]
	v_mfma_f32_16x16x32_bf16 v[60:63], v[20:23], v[36:39], v[24:27]
	v_mfma_f32_16x16x32_bf16 v[24:27], v[8:11], v[120:123], v[144:147]
	v_mfma_f32_16x16x32_bf16 v[44:47], v[12:15], v[224:227], v[24:27]
	v_mfma_f32_16x16x32_bf16 v[24:27], v[16:19], v[120:123], v[148:151]
	v_mfma_f32_16x16x32_bf16 v[40:43], v[20:23], v[224:227], v[24:27]
	v_mfma_f32_16x16x32_bf16 v[24:27], v[8:11], v[228:231], v[152:155]
	v_mfma_f32_16x16x32_bf16 v[0:3], v[8:11], v[236:239], v[0:3]
	v_mfma_f32_16x16x32_bf16 v[28:31], v[12:15], v[232:235], v[24:27]
	v_mfma_f32_16x16x32_bf16 v[24:27], v[16:19], v[228:231], v[156:159]
	v_mfma_f32_16x16x32_bf16 v[12:15], v[12:15], v[240:243], v[0:3]
	v_mfma_f32_16x16x32_bf16 v[0:3], v[16:19], v[236:239], v[4:7]
	v_mfma_f32_16x16x32_bf16 v[24:27], v[20:23], v[232:235], v[24:27]
	v_mfma_f32_16x16x32_bf16 v[8:11], v[20:23], v[240:243], v[0:3]
	v_mfma_f32_16x16x32_bf16 v[0:3], v[132:135], v[32:35], v[160:163]
	v_mfma_f32_16x16x32_bf16 v[56:59], v[212:215], v[36:39], v[0:3]
	v_mfma_f32_16x16x32_bf16 v[0:3], v[216:219], v[32:35], v[180:183]
	v_mfma_f32_16x16x32_bf16 v[48:51], v[220:223], v[36:39], v[0:3]
	v_mfma_f32_16x16x32_bf16 v[0:3], v[132:135], v[120:123], v[188:191]
	v_mfma_f32_16x16x32_bf16 v[36:39], v[212:215], v[224:227], v[0:3]
	v_mfma_f32_16x16x32_bf16 v[0:3], v[216:219], v[120:123], v[192:195]
	v_mfma_f32_16x16x32_bf16 v[32:35], v[220:223], v[224:227], v[0:3]
	v_mfma_f32_16x16x32_bf16 v[0:3], v[132:135], v[228:231], v[196:199]
	v_mfma_f32_16x16x32_bf16 v[20:23], v[212:215], v[232:235], v[0:3]
	v_mfma_f32_16x16x32_bf16 v[0:3], v[216:219], v[228:231], v[124:127]
	v_mfma_f32_16x16x32_bf16 v[16:19], v[220:223], v[232:235], v[0:3]
	v_mfma_f32_16x16x32_bf16 v[0:3], v[132:135], v[236:239], v[200:203]
	v_mfma_f32_16x16x32_bf16 v[4:7], v[212:215], v[240:243], v[0:3]
	v_mfma_f32_16x16x32_bf16 v[0:3], v[216:219], v[236:239], v[128:131]
	v_mfma_f32_16x16x32_bf16 v[0:3], v[220:223], v[240:243], v[0:3]
	s_barrier
	s_add_u32 s20, s20, 0x160180
	s_addc_u32 s21, s21, 0
	s_add_u32 s67, s22, 0x200
	s_addc_u32 s68, s23, 0
	s_mov_b32 s70, 0

; __device__ __forceinline__ int lane_id() { int l; asm volatile("v_mbcnt_lo_u32_b32 %0, -1, 0\n\tv_mbcnt_hi_u32_b32 %0, -1, %0" : "=v"(l)); return l; }
;     __device__ __forceinline__ bool next(int i, UnitG& u) const { if (!P.next(i, u)) return false; u.O = O + ((size_t)u.x0 * 256 * 2048 + (size_t)u.x1 * 256) * 2; u.ldo = 2048; u.kind = 0; return true; }
; template <class Epi, class Sched>
; __device__ __forceinline__ void gemm_phase(PG8_LAS unsigned char* lds, const Sched& S, const Epi& E, int tid_in) {
;     ...
;         int aoff, boff; { const int l3 = lane_id(), fr3 = l3 & 15, fq3 = l3 >> 4; aoff = lds_byte(wr * 64 + fr3, fq3 * 8); boff = lds_byte(wc * 32 + fr3, fq3 * 8); }
;         const bool has_next = S.next(ui + 1, nxt);
;         const char* nA = has_next ? nxt.A : cA; const char* nB = has_next ? nxt.B : cB;
;         const int nlda = has_next ? nxt.lda : cur.lda, nldb = has_next ? nxt.ldb : cur.ldb;
;         unsigned nvA, nvB; { int r2, c2; stage_rc((wid * 64 + lane_id()) * 16, r2, c2); const int rb2 = Epi::PERM ? ((r2 & ~31) + perm32(r2 & 31)) : r2;
;             nvA = (unsigned)(r2 * nlda + c2) * 2u; nvB = (unsigned)(rb2 * nldb + c2) * 2u; }
;         const unsigned nqA = (unsigned)nlda * 128u, nqB = (unsigned)nldb * 128u;
;         const int nt = cur.K / BK;
.LBB0_393:
	v_and_b32_e32 v1, 15, v0
	v_or_b32_e32 v2, s47, v1
	v_ashrrev_i32_e32 v3, 6, v0
	v_lshlrev_b32_e32 v4, 6, v2
	v_and_b32_e32 v5, 48, v0
	s_movk_i32 s53, 0x3c0
	v_lshlrev_b32_e32 v2, 2, v2
	v_and_or_b32 v4, v4, s53, v5
	v_lshl_add_u32 v6, v3, 10, s48
	v_and_b32_e32 v2, 32, v2
	v_lshlrev_b32_e32 v0, 2, v0
	s_waitcnt vmcnt(4)
	v_bitop3_b32 v32, v4, v6, v2 bitop3:0xde
	v_lshl_or_b32 v1, v1, 6, v5
	v_add_lshl_u32 v2, v3, s50, 10
	v_and_b32_e32 v0, 32, v0
	v_bitop3_b32 v137, v1, v2, v0 bitop3:0xde
	v_mbcnt_lo_u32_b32 v0, -1, 0
	v_mbcnt_hi_u32_b32 v0, -1, v0
	s_mov_b32 s53, 0xfffe0
	v_add_u32_e32 v0, s51, v0
	v_ashrrev_i32_e32 v2, 31, v0
	v_lshrrev_b32_e32 v2, 26, v2
	v_lshlrev_b32_e32 v1, 4, v0
	v_add_u32_e32 v2, v0, v2
	v_bfe_i32 v0, v0, 27, 1
	v_lshrrev_b32_e32 v0, 22, v0
	v_add_u32_e32 v0, v1, v0
	v_and_b32_e32 v0, 0xfffffc00, v0
	v_sub_u32_e32 v0, v1, v0
	v_lshrrev_b32_e32 v1, 4, v0
	v_bitop3_b32 v0, v1, v0, 32 bitop3:0x6c
	v_ashrrev_i32_e32 v3, 31, v0
	v_lshrrev_b32_e32 v3, 26, v3
	v_ashrrev_i32_e32 v2, 6, v2
	v_add_u32_e32 v3, v0, v3
	v_lshlrev_b32_e32 v1, 3, v2
	v_ashrrev_i32_e32 v4, 6, v3
	v_and_b32_e32 v3, 0xc0, v3
	v_and_b32_e32 v1, -16, v1
	v_sub_u32_e32 v0, v0, v3
	v_add_u32_e32 v1, v4, v1
	v_lshlrev_b32_e32 v2, 5, v2
	v_ashrrev_i16_sdwa v0, v205, sext(v0) dst_sel:DWORD dst_unused:UNUSED_PAD src0_sel:DWORD src1_sel:BYTE_0
	v_and_b32_e32 v2, 32, v2
	v_bfe_i32 v0, v0, 0, 16
	v_lshlrev_b32_e32 v3, 1, v1
	v_lshrrev_b32_e32 v5, 2, v1
	v_and_b32_e32 v4, 3, v4
	s_add_i32 s55, 0, 0x10000
	s_add_i32 s57, 0, 0x14000
	v_and_b32_e32 v3, 24, v3
	v_and_b32_e32 v5, 4, v5
	v_and_or_b32 v4, v1, s53, v4
	v_add_lshl_u32 v34, v2, v0, 1
	v_add_u32_e32 v134, s55, v137
	v_add_u32_e32 v135, s57, v137
	v_or3_b32 v33, v4, v5, v3
	v_lshl_add_u32 v128, v1, 12, v34
	ds_read_b128 v[0:3], v134
	ds_read_b128 v[4:7], v134 offset:1024
	ds_read_b128 v[8:11], v134 offset:2048
	ds_read_b128 v[12:15], v134 offset:3072
	ds_read_b128 v[16:19], v135
	ds_read_b128 v[20:23], v135 offset:1024
	ds_read_b128 v[24:27], v135 offset:2048
	ds_read_b128 v[28:31], v135 offset:3072
	v_lshl_add_u32 v129, v33, 12, v34
	v_mov_b32_e32 v133, v185
	v_lshl_add_u64 v[182:183], s[18:19], 0, v[132:133]
	s_add_i32 s53, s29, 0xc000
	v_add_u32_e32 v136, 0, v32
	v_lshl_add_u64 v[64:65], v[182:183], 0, s[80:81]
	s_mov_b32 m0, s53
	s_add_i32 s54, s29, 0xe000
	ds_read_b128 v[32:35], v136
	ds_read_b128 v[36:39], v136 offset:1024
	ds_read_b128 v[40:43], v136 offset:2048
	ds_read_b128 v[44:47], v136 offset:3072
	ds_read_b128 v[48:51], v136 offset:4096
	ds_read_b128 v[52:55], v136 offset:5120
	ds_read_b128 v[56:59], v136 offset:6144
	ds_read_b128 v[60:63], v136 offset:7168
	global_load_lds_dwordx4 v[64:65], off
	v_lshl_add_u64 v[64:65], v[182:183], 0, s[78:79]
	s_mov_b32 m0, s54
	s_nop 0
	global_load_lds_dwordx4 v[64:65], off
	s_waitcnt vmcnt(24)
	s_waitcnt lgkmcnt(0)
	s_barrier
	s_waitcnt lgkmcnt(0)
	v_mfma_f32_16x16x32_bf16 v[64:67], v[0:3], v[32:35], 0
	v_mfma_f32_16x16x32_bf16 v[68:71], v[8:11], v[32:35], 0
	v_mfma_f32_16x16x32_bf16 v[72:75], v[0:3], v[40:43], 0
	v_mfma_f32_16x16x32_bf16 v[76:79], v[8:11], v[40:43], 0
	v_mfma_f32_16x16x32_bf16 v[80:83], v[0:3], v[48:51], 0
	v_mfma_f32_16x16x32_bf16 v[84:87], v[8:11], v[48:51], 0
	v_mfma_f32_16x16x32_bf16 v[88:91], v[0:3], v[56:59], 0
	v_mfma_f32_16x16x32_bf16 v[92:95], v[8:11], v[56:59], 0
	v_mfma_f32_16x16x32_bf16 v[64:67], v[4:7], v[36:39], v[64:67]
	v_mfma_f32_16x16x32_bf16 v[68:71], v[12:15], v[36:39], v[68:71]
	v_mfma_f32_16x16x32_bf16 v[72:75], v[4:7], v[44:47], v[72:75]
	v_mfma_f32_16x16x32_bf16 v[76:79], v[12:15], v[44:47], v[76:79]
	v_mfma_f32_16x16x32_bf16 v[80:83], v[4:7], v[52:55], v[80:83]
	v_mfma_f32_16x16x32_bf16 v[84:87], v[12:15], v[52:55], v[84:87]
	v_mfma_f32_16x16x32_bf16 v[88:91], v[4:7], v[60:63], v[88:91]
	v_mfma_f32_16x16x32_bf16 v[92:95], v[12:15], v[60:63], v[92:95]
	v_mfma_f32_16x16x32_bf16 v[96:99], v[16:19], v[32:35], 0
	v_mfma_f32_16x16x32_bf16 v[32:35], v[24:27], v[32:35], 0
	v_mfma_f32_16x16x32_bf16 v[108:111], v[28:31], v[36:39], v[32:35]
	v_mfma_f32_16x16x32_bf16 v[32:35], v[16:19], v[40:43], 0
	v_mfma_f32_16x16x32_bf16 v[138:141], v[20:23], v[44:47], v[32:35]
	v_mfma_f32_16x16x32_bf16 v[32:35], v[24:27], v[40:43], 0
	v_mfma_f32_16x16x32_bf16 v[40:43], v[28:31], v[44:47], v[32:35]
	v_mfma_f32_16x16x32_bf16 v[32:35], v[16:19], v[48:51], 0
	v_mfma_f32_16x16x32_bf16 v[44:47], v[20:23], v[52:55], v[32:35]
	v_mfma_f32_16x16x32_bf16 v[32:35], v[24:27], v[48:51], 0
	v_mfma_f32_16x16x32_bf16 v[48:51], v[28:31], v[52:55], v[32:35]
	v_mfma_f32_16x16x32_bf16 v[32:35], v[16:19], v[56:59], 0
	v_mfma_f32_16x16x32_bf16 v[52:55], v[20:23], v[60:63], v[32:35]
	v_mfma_f32_16x16x32_bf16 v[32:35], v[24:27], v[56:59], 0
	v_mfma_f32_16x16x32_bf16 v[104:107], v[20:23], v[36:39], v[96:99]
	v_mfma_f32_16x16x32_bf16 v[56:59], v[28:31], v[60:63], v[32:35]
	s_barrier
	v_mov_b32_e32 v131, v185
	v_lshl_add_u64 v[248:249], s[20:21], 0, v[130:131]
	s_mov_b64 s[60:61], 0x100
	s_add_i32 s55, s55, s28
	v_lshl_add_u64 v[124:125], v[248:249], 0, s[60:61]
	s_mov_b32 m0, s55
	s_mov_b64 s[62:63], 0x40100
	s_add_i32 s56, s55, 0x2000
	ds_read_b128 v[32:35], v136 offset:16384
	ds_read_b128 v[36:39], v136 offset:17408
	ds_read_b128 v[60:63], v136 offset:18432
	ds_read_b128 v[96:99], v136 offset:19456
	ds_read_b128 v[100:103], v136 offset:20480
	ds_read_b128 v[112:115], v136 offset:21504
	ds_read_b128 v[116:119], v136 offset:22528
	ds_read_b128 v[120:123], v136 offset:23552
	global_load_lds_dwordx4 v[124:125], off
	v_lshl_add_u64 v[124:125], v[248:249], 0, s[62:63]
	s_mov_b32 m0, s56
	s_mov_b64 s[64:65], 0x80100
	s_add_i32 s57, s57, s28
	global_load_lds_dwordx4 v[124:125], off
	v_lshl_add_u64 v[124:125], v[248:249], 0, s[64:65]
	s_mov_b32 m0, s57
	s_mov_b64 s[66:67], 0xc0100
	s_add_i32 s58, s57, 0x2000
	global_load_lds_dwordx4 v[124:125], off
	v_lshl_add_u64 v[124:125], v[248:249], 0, s[66:67]
	s_mov_b32 m0, s58
	s_nop 0
	global_load_lds_dwordx4 v[124:125], off
	v_lshl_add_u64 v[124:125], v[182:183], 0, s[60:61]
	s_mov_b32 m0, s29
	s_nop 0
	global_load_lds_dwordx4 v[124:125], off
	v_lshl_add_u64 v[124:125], v[182:183], 0, s[62:63]
	s_mov_b32 m0, s30
	s_nop 0
	global_load_lds_dwordx4 v[124:125], off
	s_waitcnt vmcnt(24)
	s_waitcnt lgkmcnt(0)
	s_barrier
	s_waitcnt lgkmcnt(0)
	v_mfma_f32_16x16x32_bf16 v[124:127], v[0:3], v[32:35], 0
	v_mfma_f32_16x16x32_bf16 v[142:145], v[4:7], v[36:39], v[124:127]
	v_mfma_f32_16x16x32_bf16 v[124:127], v[8:11], v[32:35], 0
	v_mfma_f32_16x16x32_bf16 v[146:149], v[12:15], v[36:39], v[124:127]
	v_mfma_f32_16x16x32_bf16 v[124:127], v[0:3], v[60:63], 0
	v_mfma_f32_16x16x32_bf16 v[150:153], v[4:7], v[96:99], v[124:127]
	v_mfma_f32_16x16x32_bf16 v[124:127], v[8:11], v[60:63], 0
	v_mfma_f32_16x16x32_bf16 v[154:157], v[12:15], v[96:99], v[124:127]
	v_mfma_f32_16x16x32_bf16 v[124:127], v[0:3], v[100:103], 0
	v_mfma_f32_16x16x32_bf16 v[0:3], v[0:3], v[116:119], 0
	v_mfma_f32_16x16x32_bf16 v[158:161], v[4:7], v[112:115], v[124:127]
	v_mfma_f32_16x16x32_bf16 v[0:3], v[4:7], v[120:123], v[0:3]
	v_mfma_f32_16x16x32_bf16 v[4:7], v[8:11], v[116:119], 0
	v_mfma_f32_16x16x32_bf16 v[124:127], v[8:11], v[100:103], 0
	v_mfma_f32_16x16x32_bf16 v[8:11], v[12:15], v[120:123], v[4:7]
	v_mfma_f32_16x16x32_bf16 v[162:165], v[12:15], v[112:115], v[124:127]
	v_mfma_f32_16x16x32_bf16 v[4:7], v[16:19], v[32:35], 0
	v_mfma_f32_16x16x32_bf16 v[12:15], v[20:23], v[36:39], v[4:7]
	v_mfma_f32_16x16x32_bf16 v[4:7], v[24:27], v[32:35], 0
	v_mfma_f32_16x16x32_bf16 v[166:169], v[28:31], v[36:39], v[4:7]
	v_mfma_f32_16x16x32_bf16 v[4:7], v[16:19], v[60:63], 0
	v_mfma_f32_16x16x32_bf16 v[170:173], v[20:23], v[96:99], v[4:7]
	v_mfma_f32_16x16x32_bf16 v[4:7], v[24:27], v[60:63], 0
	v_mfma_f32_16x16x32_bf16 v[174:177], v[28:31], v[96:99], v[4:7]
	v_mfma_f32_16x16x32_bf16 v[4:7], v[16:19], v[100:103], 0
	v_mfma_f32_16x16x32_bf16 v[178:181], v[20:23], v[112:115], v[4:7]
	v_mfma_f32_16x16x32_bf16 v[4:7], v[24:27], v[100:103], 0
	v_mfma_f32_16x16x32_bf16 v[188:191], v[28:31], v[112:115], v[4:7]
	v_mfma_f32_16x16x32_bf16 v[4:7], v[16:19], v[116:119], 0
	v_mfma_f32_16x16x32_bf16 v[192:195], v[20:23], v[120:123], v[4:7]
	v_mfma_f32_16x16x32_bf16 v[4:7], v[24:27], v[116:119], 0
	v_mfma_f32_16x16x32_bf16 v[196:199], v[28:31], v[120:123], v[4:7]
	s_barrier
	s_add_i32 s59, 0, 0x18000
	s_add_i32 s61, 0, 0x1c000
	v_add_u32_e32 v131, s59, v137
	v_add_u32_e32 v137, s61, v137
	s_nop 0
	ds_read_b128 v[4:7], v131
	ds_read_b128 v[24:27], v131 offset:1024
	ds_read_b128 v[28:31], v131 offset:2048
	ds_read_b128 v[60:63], v131 offset:3072
	ds_read_b128 v[200:203], v137
	ds_read_b128 v[212:215], v137 offset:1024
	ds_read_b128 v[216:219], v137 offset:2048
	ds_read_b128 v[220:223], v137 offset:3072
	s_mov_b32 m0, s31
	v_lshl_add_u64 v[32:33], v[182:183], 0, s[64:65]
	ds_read_b128 v[16:19], v136 offset:32768
	ds_read_b128 v[20:23], v136 offset:33792
	ds_read_b128 v[224:227], v136 offset:34816
	ds_read_b128 v[228:231], v136 offset:35840
	ds_read_b128 v[232:235], v136 offset:36864
	ds_read_b128 v[236:239], v136 offset:37888
	ds_read_b128 v[240:243], v136 offset:38912
	ds_read_b128 v[244:247], v136 offset:39936
	global_load_lds_dwordx4 v[32:33], off
	v_lshl_add_u64 v[32:33], v[182:183], 0, s[66:67]
	s_mov_b32 m0, s34
	s_nop 0
	global_load_lds_dwordx4 v[32:33], off
	s_waitcnt vmcnt(8)
	s_waitcnt lgkmcnt(0)
	s_barrier
	s_waitcnt lgkmcnt(0)
	v_mfma_f32_16x16x32_bf16 v[32:35], v[4:7], v[16:19], v[64:67]
	v_mfma_f32_16x16x32_bf16 v[116:119], v[24:27], v[20:23], v[32:35]
	v_mfma_f32_16x16x32_bf16 v[32:35], v[28:31], v[16:19], v[68:71]
	v_mfma_f32_16x16x32_bf16 v[112:115], v[60:63], v[20:23], v[32:35]
	v_mfma_f32_16x16x32_bf16 v[32:35], v[4:7], v[224:227], v[72:75]
	v_mfma_f32_16x16x32_bf16 v[100:103], v[24:27], v[228:231], v[32:35]
	v_mfma_f32_16x16x32_bf16 v[32:35], v[28:31], v[224:227], v[76:79]
	v_mfma_f32_16x16x32_bf16 v[96:99], v[60:63], v[228:231], v[32:35]
	v_mfma_f32_16x16x32_bf16 v[32:35], v[4:7], v[232:235], v[80:83]
	v_mfma_f32_16x16x32_bf16 v[68:71], v[24:27], v[236:239], v[32:35]
	v_mfma_f32_16x16x32_bf16 v[32:35], v[28:31], v[232:235], v[84:87]
	v_mfma_f32_16x16x32_bf16 v[64:67], v[60:63], v[236:239], v[32:35]
	v_mfma_f32_16x16x32_bf16 v[32:35], v[4:7], v[240:243], v[88:91]
	v_mfma_f32_16x16x32_bf16 v[36:39], v[24:27], v[244:247], v[32:35]
	v_mfma_f32_16x16x32_bf16 v[32:35], v[28:31], v[240:243], v[92:95]
	v_mfma_f32_16x16x32_bf16 v[32:35], v[60:63], v[244:247], v[32:35]
	v_mfma_f32_16x16x32_bf16 v[72:75], v[200:203], v[16:19], v[104:107]
	v_mfma_f32_16x16x32_bf16 v[16:19], v[216:219], v[16:19], v[108:111]
	v_mfma_f32_16x16x32_bf16 v[120:123], v[220:223], v[20:23], v[16:19]
	v_mfma_f32_16x16x32_bf16 v[16:19], v[200:203], v[224:227], v[138:141]
	v_mfma_f32_16x16x32_bf16 v[108:111], v[212:215], v[228:231], v[16:19]
	v_mfma_f32_16x16x32_bf16 v[16:19], v[216:219], v[224:227], v[40:43]
	v_mfma_f32_16x16x32_bf16 v[104:107], v[220:223], v[228:231], v[16:19]
	v_mfma_f32_16x16x32_bf16 v[16:19], v[200:203], v[232:235], v[44:47]
	v_mfma_f32_16x16x32_bf16 v[76:79], v[212:215], v[236:239], v[16:19]
	v_mfma_f32_16x16x32_bf16 v[16:19], v[216:219], v[232:235], v[48:51]
	v_mfma_f32_16x16x32_bf16 v[124:127], v[212:215], v[20:23], v[72:75]
	v_mfma_f32_16x16x32_bf16 v[72:75], v[220:223], v[236:239], v[16:19]
	v_mfma_f32_16x16x32_bf16 v[16:19], v[200:203], v[240:243], v[52:55]
	v_mfma_f32_16x16x32_bf16 v[44:47], v[212:215], v[244:247], v[16:19]
	v_mfma_f32_16x16x32_bf16 v[16:19], v[216:219], v[240:243], v[56:59]
	v_mfma_f32_16x16x32_bf16 v[40:43], v[220:223], v[244:247], v[16:19]
	s_barrier
; #define PG8_WAIT_VP() asm volatile("s_waitcnt vmcnt(%0)" :: "n"(8 + Epi::NST) : "memory")
; template <class Epi, class Sched>
; __device__ __forceinline__ void gemm_phase(PG8_LAS unsigned char* lds, const Sched& S, const Epi& E, int tid_in) {
;     ...
;         { const int t = 0; PG8_KITER(PG8_WAIT_VP()); }
	s_mov_b64 s[64:65], 0x180
	s_add_i32 s59, s59, s28
	s_nop 2
	v_lshl_add_u64 v[16:17], v[248:249], 0, s[64:65]
	s_mov_b32 m0, s59
	s_mov_b64 s[66:67], 0x40180
	s_add_i32 s60, s59, 0x2000
	ds_read_b128 v[56:59], v136 offset:49152
	ds_read_b128 v[88:91], v136 offset:50176
	ds_read_b128 v[138:141], v136 offset:51200
	ds_read_b128 v[224:227], v136 offset:52224
	ds_read_b128 v[228:231], v136 offset:53248
	ds_read_b128 v[232:235], v136 offset:54272
	ds_read_b128 v[236:239], v136 offset:55296
	ds_read_b128 v[240:243], v136 offset:56320
	global_load_lds_dwordx4 v[16:17], off
	v_lshl_add_u64 v[16:17], v[248:249], 0, s[66:67]
	s_mov_b32 m0, s60
	s_add_i32 s61, s61, s28
	global_load_lds_dwordx4 v[16:17], off
	v_lshl_add_u64 v[16:17], v[248:249], 0, s[70:71]
	s_mov_b32 m0, s61
	s_add_i32 s62, s61, 0x2000
	global_load_lds_dwordx4 v[16:17], off
	v_lshl_add_u64 v[16:17], v[248:249], 0, s[72:73]
	s_mov_b32 m0, s62
	s_nop 0
	global_load_lds_dwordx4 v[16:17], off
	v_lshl_add_u64 v[16:17], v[182:183], 0, s[64:65]
	s_mov_b32 m0, s45
	s_nop 0
	global_load_lds_dwordx4 v[16:17], off
	v_lshl_add_u64 v[16:17], v[182:183], 0, s[66:67]
	s_mov_b32 m0, s46
	s_nop 0
	global_load_lds_dwordx4 v[16:17], off
	s_waitcnt vmcnt(8)
	s_waitcnt lgkmcnt(0)
	s_barrier
	s_waitcnt lgkmcnt(0)
	v_mfma_f32_16x16x32_bf16 v[16:19], v[4:7], v[56:59], v[142:145]
	v_mfma_f32_16x16x32_bf16 v[84:87], v[24:27], v[88:91], v[16:19]
	v_mfma_f32_16x16x32_bf16 v[16:19], v[28:31], v[56:59], v[146:149]
	v_mfma_f32_16x16x32_bf16 v[80:83], v[60:63], v[88:91], v[16:19]
	v_mfma_f32_16x16x32_bf16 v[16:19], v[4:7], v[138:141], v[150:153]
	v_mfma_f32_16x16x32_bf16 v[52:55], v[24:27], v[224:227], v[16:19]
	v_mfma_f32_16x16x32_bf16 v[16:19], v[28:31], v[138:141], v[154:157]
	v_mfma_f32_16x16x32_bf16 v[48:51], v[60:63], v[224:227], v[16:19]
	v_mfma_f32_16x16x32_bf16 v[16:19], v[4:7], v[228:231], v[158:161]
	v_mfma_f32_16x16x32_bf16 v[0:3], v[4:7], v[236:239], v[0:3]
	v_mfma_f32_16x16x32_bf16 v[20:23], v[24:27], v[232:235], v[16:19]
	v_mfma_f32_16x16x32_bf16 v[16:19], v[28:31], v[228:231], v[162:165]
	v_mfma_f32_16x16x32_bf16 v[4:7], v[24:27], v[240:243], v[0:3]
	v_mfma_f32_16x16x32_bf16 v[0:3], v[28:31], v[236:239], v[8:11]
	v_mfma_f32_16x16x32_bf16 v[16:19], v[60:63], v[232:235], v[16:19]
	v_mfma_f32_16x16x32_bf16 v[0:3], v[60:63], v[240:243], v[0:3]
	v_mfma_f32_16x16x32_bf16 v[8:11], v[200:203], v[56:59], v[12:15]
	v_mfma_f32_16x16x32_bf16 v[92:95], v[212:215], v[88:91], v[8:11]
	v_mfma_f32_16x16x32_bf16 v[8:11], v[216:219], v[56:59], v[166:169]
	v_mfma_f32_16x16x32_bf16 v[88:91], v[220:223], v[88:91], v[8:11]
	v_mfma_f32_16x16x32_bf16 v[8:11], v[200:203], v[138:141], v[170:173]
	v_mfma_f32_16x16x32_bf16 v[60:63], v[212:215], v[224:227], v[8:11]
	v_mfma_f32_16x16x32_bf16 v[8:11], v[216:219], v[138:141], v[174:177]
	v_mfma_f32_16x16x32_bf16 v[56:59], v[220:223], v[224:227], v[8:11]
	v_mfma_f32_16x16x32_bf16 v[8:11], v[200:203], v[228:231], v[178:181]
	v_mfma_f32_16x16x32_bf16 v[28:31], v[212:215], v[232:235], v[8:11]
	v_mfma_f32_16x16x32_bf16 v[8:11], v[216:219], v[228:231], v[188:191]
	v_mfma_f32_16x16x32_bf16 v[24:27], v[220:223], v[232:235], v[8:11]
	v_mfma_f32_16x16x32_bf16 v[8:11], v[200:203], v[236:239], v[192:195]
	v_mfma_f32_16x16x32_bf16 v[12:15], v[212:215], v[240:243], v[8:11]
	v_mfma_f32_16x16x32_bf16 v[8:11], v[216:219], v[236:239], v[196:199]
	v_mfma_f32_16x16x32_bf16 v[8:11], v[220:223], v[240:243], v[8:11]
	s_barrier
	s_add_u32 s18, s18, 0x80180
	s_addc_u32 s19, s19, 0
	s_add_u32 s63, s20, 0x200
	s_addc_u32 s64, s21, 0
	s_mov_b32 s65, 0

; __device__ __forceinline__ int lane_id() { int l; asm volatile("v_mbcnt_lo_u32_b32 %0, -1, 0\n\tv_mbcnt_hi_u32_b32 %0, -1, %0" : "=v"(l)); return l; }
;     __device__ __forceinline__ bool next(int i, UnitG& u) const { if (!P.next(i, u)) return false; u.O = O + ((size_t)u.x0 * 256 * 2048 + (size_t)u.x1 * 256) * 2; u.ldo = 2048; u.kind = 0; return true; }
; template <class Epi, class Sched>
; __device__ __forceinline__ void gemm_phase(PG8_LAS unsigned char* lds, const Sched& S, const Epi& E, int tid_in) {
;     ...
;         int aoff, boff; { const int l3 = lane_id(), fr3 = l3 & 15, fq3 = l3 >> 4; aoff = lds_byte(wr * 64 + fr3, fq3 * 8); boff = lds_byte(wc * 32 + fr3, fq3 * 8); }
;         const bool has_next = S.next(ui + 1, nxt);
;         const char* nA = has_next ? nxt.A : cA; const char* nB = has_next ? nxt.B : cB;
;         const int nlda = has_next ? nxt.lda : cur.lda, nldb = has_next ? nxt.ldb : cur.ldb;
;         unsigned nvA, nvB; { int r2, c2; stage_rc((wid * 64 + lane_id()) * 16, r2, c2); const int rb2 = Epi::PERM ? ((r2 & ~31) + perm32(r2 & 31)) : r2;
;             nvA = (unsigned)(r2 * nlda + c2) * 2u; nvB = (unsigned)(rb2 * nldb + c2) * 2u; }
;         const unsigned nqA = (unsigned)nlda * 128u, nqB = (unsigned)nldb * 128u;
;         const int nt = cur.K / BK;
.LBB0_541:
	v_and_b32_e32 v1, 15, v0
	v_or_b32_e32 v2, s56, v1
	v_ashrrev_i32_e32 v3, 6, v0
	v_lshlrev_b32_e32 v4, 6, v2
	v_and_b32_e32 v5, 48, v0
	s_movk_i32 s22, 0x3c0
	v_lshlrev_b32_e32 v2, 2, v2
	v_and_or_b32 v4, v4, s22, v5
	v_lshl_add_u32 v6, v3, 10, s57
	v_and_b32_e32 v2, 32, v2
	v_lshlrev_b32_e32 v0, 2, v0
	s_waitcnt vmcnt(4)
	v_bitop3_b32 v32, v4, v6, v2 bitop3:0xde
	v_lshl_or_b32 v1, v1, 6, v5
	v_add_lshl_u32 v2, v3, s59, 10
	v_and_b32_e32 v0, 32, v0
	v_bitop3_b32 v186, v1, v2, v0 bitop3:0xde
	v_mbcnt_lo_u32_b32 v0, -1, 0
	v_mbcnt_hi_u32_b32 v0, -1, v0
	s_mov_b32 s22, 0x1ffffe0
	v_add_u32_e32 v0, s60, v0
	v_ashrrev_i32_e32 v2, 31, v0
	v_lshrrev_b32_e32 v2, 26, v2
	v_lshlrev_b32_e32 v1, 4, v0
	v_add_u32_e32 v2, v0, v2
	v_bfe_i32 v0, v0, 27, 1
	v_lshrrev_b32_e32 v0, 22, v0
	v_add_u32_e32 v0, v1, v0
	v_and_b32_e32 v0, 0xfffffc00, v0
	v_sub_u32_e32 v0, v1, v0
	v_lshrrev_b32_e32 v1, 4, v0
	v_bitop3_b32 v0, v1, v0, 32 bitop3:0x6c
	v_ashrrev_i32_e32 v3, 31, v0
	v_lshrrev_b32_e32 v3, 26, v3
	v_ashrrev_i32_e32 v2, 6, v2
	v_add_u32_e32 v3, v0, v3
	v_lshlrev_b32_e32 v1, 3, v2
	v_ashrrev_i32_e32 v4, 6, v3
	v_and_b32_e32 v3, 0xc0, v3
	v_and_b32_e32 v1, -16, v1
	v_lshlrev_b32_e32 v2, 5, v2
	v_sub_u32_e32 v0, v0, v3
	v_add_u32_e32 v1, v4, v1
	v_and_b32_e32 v2, 32, v2
	v_ashrrev_i16_sdwa v0, v205, sext(v0) dst_sel:DWORD dst_unused:UNUSED_PAD src0_sel:DWORD src1_sel:BYTE_0
	v_add_u32_sdwa v68, v2, sext(v0) dst_sel:DWORD dst_unused:UNUSED_PAD src0_sel:DWORD src1_sel:WORD_0
	v_lshlrev_b32_e32 v0, 1, v1
	v_lshrrev_b32_e32 v2, 2, v1
	v_and_b32_e32 v3, 3, v4
	v_and_b32_e32 v0, 24, v0
	v_and_b32_e32 v2, 4, v2
	v_and_or_b32 v3, v1, s22, v3
	v_or3_b32 v0, v3, v2, v0
	s_movk_i32 s22, 0x180
	v_mul_lo_u32 v69, v1, s22
	v_mul_lo_u32 v0, v0, s22
	s_add_i32 s22, 0, 0x10000
	s_add_i32 s23, 0, 0x14000
	v_add_u32_e32 v12, s22, v186
	v_add_u32_e32 v28, s23, v186
	v_add_lshl_u32 v128, v0, v68, 1
	ds_read_b128 v[0:3], v12
	ds_read_b128 v[4:7], v12 offset:1024
	ds_read_b128 v[8:11], v12 offset:2048
	ds_read_b128 v[12:15], v12 offset:3072
	ds_read_b128 v[16:19], v28
	ds_read_b128 v[20:23], v28 offset:1024
	ds_read_b128 v[24:27], v28 offset:2048
	ds_read_b128 v[28:31], v28 offset:3072
	v_lshl_add_u64 v[64:65], s[20:21], 0, v[184:185]
	s_mov_b64 s[66:67], 0x18080
	v_add_u32_e32 v187, 0, v32
	v_lshl_add_u64 v[66:67], v[64:65], 0, s[66:67]
	s_add_i32 m0, s49, 0xc000
	s_mov_b64 s[70:71], 0x24080
	ds_read_b128 v[32:35], v187
	ds_read_b128 v[36:39], v187 offset:1024
	ds_read_b128 v[40:43], v187 offset:2048
	ds_read_b128 v[44:47], v187 offset:3072
	ds_read_b128 v[48:51], v187 offset:4096
	ds_read_b128 v[52:55], v187 offset:5120
	ds_read_b128 v[56:59], v187 offset:6144
	ds_read_b128 v[60:63], v187 offset:7168
	global_load_lds_dwordx4 v[66:67], off
	v_lshl_add_u64 v[64:65], v[64:65], 0, s[70:71]
	s_add_i32 m0, s49, 0xe000
	v_add_lshl_u32 v134, v68, v69, 1
	global_load_lds_dwordx4 v[64:65], off
	s_waitcnt vmcnt(24)
	s_waitcnt lgkmcnt(0)
	s_barrier
	s_waitcnt lgkmcnt(0)
	v_mfma_f32_16x16x32_bf16 v[88:91], v[0:3], v[56:59], 0
	v_mfma_f32_16x16x32_bf16 v[64:67], v[0:3], v[32:35], 0
	v_mfma_f32_16x16x32_bf16 v[68:71], v[8:11], v[32:35], 0
	v_mfma_f32_16x16x32_bf16 v[72:75], v[0:3], v[40:43], 0
	v_mfma_f32_16x16x32_bf16 v[76:79], v[8:11], v[40:43], 0
	v_mfma_f32_16x16x32_bf16 v[80:83], v[0:3], v[48:51], 0
	v_mfma_f32_16x16x32_bf16 v[84:87], v[8:11], v[48:51], 0
	v_mfma_f32_16x16x32_bf16 v[96:99], v[4:7], v[60:63], v[88:91]
	v_mfma_f32_16x16x32_bf16 v[88:91], v[8:11], v[56:59], 0
	v_mfma_f32_16x16x32_bf16 v[64:67], v[4:7], v[36:39], v[64:67]
	v_mfma_f32_16x16x32_bf16 v[68:71], v[12:15], v[36:39], v[68:71]
	v_mfma_f32_16x16x32_bf16 v[72:75], v[4:7], v[44:47], v[72:75]
	v_mfma_f32_16x16x32_bf16 v[76:79], v[12:15], v[44:47], v[76:79]
	v_mfma_f32_16x16x32_bf16 v[80:83], v[4:7], v[52:55], v[80:83]
	v_mfma_f32_16x16x32_bf16 v[84:87], v[12:15], v[52:55], v[84:87]
	v_mfma_f32_16x16x32_bf16 v[100:103], v[12:15], v[60:63], v[88:91]
	v_mfma_f32_16x16x32_bf16 v[88:91], v[16:19], v[32:35], 0
	v_mfma_f32_16x16x32_bf16 v[32:35], v[24:27], v[32:35], 0
	v_mfma_f32_16x16x32_bf16 v[112:115], v[20:23], v[36:39], v[88:91]
	v_mfma_f32_16x16x32_bf16 v[32:35], v[28:31], v[36:39], v[32:35]
	v_mfma_f32_16x16x32_bf16 v[36:39], v[16:19], v[40:43], 0
	v_mfma_f32_16x16x32_bf16 v[40:43], v[24:27], v[40:43], 0
	v_mfma_f32_16x16x32_bf16 v[36:39], v[20:23], v[44:47], v[36:39]
	v_mfma_f32_16x16x32_bf16 v[40:43], v[28:31], v[44:47], v[40:43]
	v_mfma_f32_16x16x32_bf16 v[44:47], v[16:19], v[48:51], 0
	v_mfma_f32_16x16x32_bf16 v[48:51], v[24:27], v[48:51], 0
	v_mfma_f32_16x16x32_bf16 v[44:47], v[20:23], v[52:55], v[44:47]
	v_mfma_f32_16x16x32_bf16 v[48:51], v[28:31], v[52:55], v[48:51]
	v_mfma_f32_16x16x32_bf16 v[52:55], v[16:19], v[56:59], 0
	v_mfma_f32_16x16x32_bf16 v[56:59], v[24:27], v[56:59], 0
	v_mfma_f32_16x16x32_bf16 v[52:55], v[20:23], v[60:63], v[52:55]
	v_mfma_f32_16x16x32_bf16 v[56:59], v[28:31], v[60:63], v[56:59]
	s_barrier
	v_mov_b32_e32 v129, v185
	s_add_i32 s20, s22, s47
	v_lshl_add_u64 v[240:241], s[8:9], 0, v[128:129]
	s_mov_b32 m0, s20
	s_mov_b64 s[24:25], 0xc000
	ds_read_b128 v[60:63], v187 offset:16384
	ds_read_b128 v[88:91], v187 offset:17408
	ds_read_b128 v[92:95], v187 offset:18432
	ds_read_b128 v[104:107], v187 offset:19456
	ds_read_b128 v[108:111], v187 offset:20480
	ds_read_b128 v[116:119], v187 offset:21504
	ds_read_b128 v[120:123], v187 offset:22528
	ds_read_b128 v[124:127], v187 offset:23552
	global_load_lds_dwordx4 v128, s[8:9]
	v_lshl_add_u64 v[128:129], v[240:241], 0, s[24:25]
	s_add_i32 m0, s20, 0x2000
	s_mov_b64 s[64:65], 0x18000
	s_add_i32 s20, s23, s47
	global_load_lds_dwordx4 v[128:129], off
	v_lshl_add_u64 v[128:129], v[240:241], 0, s[64:65]
	s_mov_b32 m0, s20
	s_mov_b64 s[22:23], 0x24000
	global_load_lds_dwordx4 v[128:129], off
	v_lshl_add_u64 v[128:129], v[240:241], 0, s[22:23]
	s_add_i32 m0, s20, 0x2000
	v_mov_b32_e32 v135, v185
	global_load_lds_dwordx4 v[128:129], off
	v_lshl_add_u64 v[242:243], s[16:17], 0, v[134:135]
	s_mov_b32 m0, s49
	v_lshl_add_u64 v[128:129], v[242:243], 0, s[24:25]
	global_load_lds_dwordx4 v134, s[16:17]
	s_mov_b32 m0, s51
	s_nop 0
	global_load_lds_dwordx4 v[128:129], off
	s_waitcnt vmcnt(24)
	s_waitcnt lgkmcnt(0)
	s_barrier
	s_waitcnt lgkmcnt(0)
	v_mfma_f32_16x16x32_bf16 v[128:131], v[0:3], v[60:63], 0
	v_mfma_f32_16x16x32_bf16 v[140:143], v[0:3], v[92:95], 0
	v_mfma_f32_16x16x32_bf16 v[148:151], v[0:3], v[108:111], 0
	v_mfma_f32_16x16x32_bf16 v[0:3], v[0:3], v[120:123], 0
	v_mfma_f32_16x16x32_bf16 v[128:131], v[4:7], v[88:91], v[128:131]
	v_mfma_f32_16x16x32_bf16 v[140:143], v[4:7], v[104:107], v[140:143]
	v_mfma_f32_16x16x32_bf16 v[148:151], v[4:7], v[116:119], v[148:151]
	v_mfma_f32_16x16x32_bf16 v[0:3], v[4:7], v[124:127], v[0:3]
	v_mfma_f32_16x16x32_bf16 v[4:7], v[8:11], v[120:123], 0
	v_mfma_f32_16x16x32_bf16 v[136:139], v[8:11], v[60:63], 0
	v_mfma_f32_16x16x32_bf16 v[144:147], v[8:11], v[92:95], 0
	v_mfma_f32_16x16x32_bf16 v[152:155], v[8:11], v[108:111], 0
	v_mfma_f32_16x16x32_bf16 v[4:7], v[12:15], v[124:127], v[4:7]
	v_mfma_f32_16x16x32_bf16 v[136:139], v[12:15], v[88:91], v[136:139]
	v_mfma_f32_16x16x32_bf16 v[144:147], v[12:15], v[104:107], v[144:147]
	v_mfma_f32_16x16x32_bf16 v[152:155], v[12:15], v[116:119], v[152:155]
	v_mfma_f32_16x16x32_bf16 v[8:11], v[16:19], v[60:63], 0
	v_mfma_f32_16x16x32_bf16 v[156:159], v[20:23], v[88:91], v[8:11]
	v_mfma_f32_16x16x32_bf16 v[8:11], v[24:27], v[60:63], 0
	v_mfma_f32_16x16x32_bf16 v[160:163], v[28:31], v[88:91], v[8:11]
	v_mfma_f32_16x16x32_bf16 v[8:11], v[16:19], v[92:95], 0
	v_mfma_f32_16x16x32_bf16 v[164:167], v[20:23], v[104:107], v[8:11]
	v_mfma_f32_16x16x32_bf16 v[8:11], v[24:27], v[92:95], 0
	v_mfma_f32_16x16x32_bf16 v[168:171], v[28:31], v[104:107], v[8:11]
	v_mfma_f32_16x16x32_bf16 v[8:11], v[16:19], v[108:111], 0
	v_mfma_f32_16x16x32_bf16 v[172:175], v[20:23], v[116:119], v[8:11]
	v_mfma_f32_16x16x32_bf16 v[8:11], v[24:27], v[108:111], 0
	v_mfma_f32_16x16x32_bf16 v[176:179], v[28:31], v[116:119], v[8:11]
	v_mfma_f32_16x16x32_bf16 v[8:11], v[16:19], v[120:123], 0
	v_mfma_f32_16x16x32_bf16 v[180:183], v[20:23], v[124:127], v[8:11]
	v_mfma_f32_16x16x32_bf16 v[8:11], v[24:27], v[120:123], 0
	v_mfma_f32_16x16x32_bf16 v[188:191], v[28:31], v[124:127], v[8:11]
	s_barrier
	s_add_i32 s20, 0, 0x18000
	s_add_i32 s21, 0, 0x1c000
	v_add_u32_e32 v20, s20, v186
	v_add_u32_e32 v24, s21, v186
	s_nop 0
	ds_read_b128 v[8:11], v20
	ds_read_b128 v[12:15], v20 offset:1024
	ds_read_b128 v[16:19], v20 offset:2048
	ds_read_b128 v[20:23], v20 offset:3072
	ds_read_b128 v[192:195], v24
	ds_read_b128 v[196:199], v24 offset:1024
	ds_read_b128 v[200:203], v24 offset:2048
	ds_read_b128 v[212:215], v24 offset:3072
	s_mov_b32 m0, s52
	v_lshl_add_u64 v[88:89], v[242:243], 0, s[64:65]
	ds_read_b128 v[24:27], v187 offset:32768
	ds_read_b128 v[28:31], v187 offset:33792
	ds_read_b128 v[60:63], v187 offset:34816
	ds_read_b128 v[216:219], v187 offset:35840
	ds_read_b128 v[220:223], v187 offset:36864
	ds_read_b128 v[224:227], v187 offset:37888
	ds_read_b128 v[228:231], v187 offset:38912
	ds_read_b128 v[232:235], v187 offset:39936
	global_load_lds_dwordx4 v[88:89], off
	v_lshl_add_u64 v[88:89], v[242:243], 0, s[22:23]
	s_mov_b32 m0, s53
	s_nop 0
	global_load_lds_dwordx4 v[88:89], off
	s_waitcnt vmcnt(8)
	s_waitcnt lgkmcnt(0)
	s_barrier
	s_waitcnt lgkmcnt(0)
	v_mfma_f32_16x16x32_bf16 v[64:67], v[8:11], v[24:27], v[64:67]
	v_mfma_f32_16x16x32_bf16 v[124:127], v[12:15], v[28:31], v[64:67]
	v_mfma_f32_16x16x32_bf16 v[64:67], v[16:19], v[24:27], v[68:71]
	v_mfma_f32_16x16x32_bf16 v[120:123], v[20:23], v[28:31], v[64:67]
	v_mfma_f32_16x16x32_bf16 v[64:67], v[8:11], v[60:63], v[72:75]
	v_mfma_f32_16x16x32_bf16 v[108:111], v[12:15], v[216:219], v[64:67]
	v_mfma_f32_16x16x32_bf16 v[64:67], v[16:19], v[60:63], v[76:79]
	v_mfma_f32_16x16x32_bf16 v[104:107], v[20:23], v[216:219], v[64:67]
	v_mfma_f32_16x16x32_bf16 v[64:67], v[8:11], v[220:223], v[80:83]
	v_mfma_f32_16x16x32_bf16 v[92:95], v[12:15], v[224:227], v[64:67]
	v_mfma_f32_16x16x32_bf16 v[64:67], v[16:19], v[220:223], v[84:87]
	v_mfma_f32_16x16x32_bf16 v[88:91], v[20:23], v[224:227], v[64:67]
	v_mfma_f32_16x16x32_bf16 v[64:67], v[8:11], v[228:231], v[96:99]
	v_mfma_f32_16x16x32_bf16 v[76:79], v[12:15], v[232:235], v[64:67]
	v_mfma_f32_16x16x32_bf16 v[64:67], v[16:19], v[228:231], v[100:103]
	v_mfma_f32_16x16x32_bf16 v[72:75], v[20:23], v[232:235], v[64:67]
	v_mfma_f32_16x16x32_bf16 v[64:67], v[192:195], v[24:27], v[112:115]
	v_mfma_f32_16x16x32_bf16 v[24:27], v[200:203], v[24:27], v[32:35]
	v_mfma_f32_16x16x32_bf16 v[112:115], v[212:215], v[28:31], v[24:27]
	v_mfma_f32_16x16x32_bf16 v[24:27], v[192:195], v[60:63], v[36:39]
	v_mfma_f32_16x16x32_bf16 v[100:103], v[196:199], v[216:219], v[24:27]
	v_mfma_f32_16x16x32_bf16 v[24:27], v[200:203], v[60:63], v[40:43]
	v_mfma_f32_16x16x32_bf16 v[96:99], v[212:215], v[216:219], v[24:27]
	v_mfma_f32_16x16x32_bf16 v[24:27], v[192:195], v[220:223], v[44:47]
	v_mfma_f32_16x16x32_bf16 v[84:87], v[196:199], v[224:227], v[24:27]
	v_mfma_f32_16x16x32_bf16 v[24:27], v[200:203], v[220:223], v[48:51]
	v_mfma_f32_16x16x32_bf16 v[80:83], v[212:215], v[224:227], v[24:27]
	v_mfma_f32_16x16x32_bf16 v[24:27], v[192:195], v[228:231], v[52:55]
	v_mfma_f32_16x16x32_bf16 v[68:71], v[196:199], v[232:235], v[24:27]
	v_mfma_f32_16x16x32_bf16 v[24:27], v[200:203], v[228:231], v[56:59]
	v_mfma_f32_16x16x32_bf16 v[116:119], v[196:199], v[28:31], v[64:67]
	v_mfma_f32_16x16x32_bf16 v[64:67], v[212:215], v[232:235], v[24:27]
	s_barrier
; #define PG8_WAIT_V(n) asm volatile("s_waitcnt vmcnt(" #n ")" ::: "memory")
; #define PG8_WAIT_VP() asm volatile("s_waitcnt vmcnt(%0)" :: "n"(8 + Epi::NST) : "memory")
; #define PG8_BAR __builtin_amdgcn_s_barrier()
; template <class Epi, class Sched>
; __device__ __forceinline__ void gemm_phase(PG8_LAS unsigned char* lds, const Sched& S, const Epi& E, int tid_in) {
;     ...
;         { const int t = 0; PG8_KITER(PG8_WAIT_VP()); }
;         for (int t = 2; t < nt; t += 2) PG8_KITER(PG8_WAIT_V(8));
;     ...
;         if (wr == 0) PG8_BAR;
	s_add_i32 s20, s20, s47
	s_nop 2
	v_lshl_add_u64 v[24:25], v[240:241], 0, s[84:85]
	s_mov_b32 m0, s20
	s_mov_b64 s[22:23], 0xc080
	ds_read_b128 v[32:35], v187 offset:49152
	ds_read_b128 v[36:39], v187 offset:50176
	ds_read_b128 v[216:219], v187 offset:51200
	ds_read_b128 v[220:223], v187 offset:52224
	ds_read_b128 v[224:227], v187 offset:53248
	ds_read_b128 v[228:231], v187 offset:54272
	ds_read_b128 v[232:235], v187 offset:55296
	ds_read_b128 v[236:239], v187 offset:56320
	global_load_lds_dwordx4 v[24:25], off
	v_lshl_add_u64 v[24:25], v[240:241], 0, s[22:23]
	s_add_i32 m0, s20, 0x2000
	s_add_i32 s20, s21, s47
	global_load_lds_dwordx4 v[24:25], off
	v_lshl_add_u64 v[24:25], v[240:241], 0, s[66:67]
	s_mov_b32 m0, s20
	s_nop 0
	global_load_lds_dwordx4 v[24:25], off
	v_lshl_add_u64 v[24:25], v[240:241], 0, s[70:71]
	s_add_i32 m0, s20, 0x2000
	s_nop 0
	global_load_lds_dwordx4 v[24:25], off
	v_lshl_add_u64 v[24:25], v[242:243], 0, s[84:85]
	s_mov_b32 m0, s54
	s_nop 0
	global_load_lds_dwordx4 v[24:25], off
	v_lshl_add_u64 v[24:25], v[242:243], 0, s[22:23]
	s_mov_b32 m0, s55
	s_nop 0
	global_load_lds_dwordx4 v[24:25], off
	s_waitcnt vmcnt(8)
	s_waitcnt lgkmcnt(0)
	s_barrier
	s_waitcnt lgkmcnt(0)
	v_mfma_f32_16x16x32_bf16 v[24:27], v[8:11], v[32:35], v[128:131]
	v_mfma_f32_16x16x32_bf16 v[60:63], v[12:15], v[36:39], v[24:27]
	v_mfma_f32_16x16x32_bf16 v[24:27], v[16:19], v[32:35], v[136:139]
	v_mfma_f32_16x16x32_bf16 v[56:59], v[20:23], v[36:39], v[24:27]
	v_mfma_f32_16x16x32_bf16 v[24:27], v[8:11], v[216:219], v[140:143]
	v_mfma_f32_16x16x32_bf16 v[44:47], v[12:15], v[220:223], v[24:27]
	v_mfma_f32_16x16x32_bf16 v[24:27], v[16:19], v[216:219], v[144:147]
	v_mfma_f32_16x16x32_bf16 v[40:43], v[20:23], v[220:223], v[24:27]
	v_mfma_f32_16x16x32_bf16 v[24:27], v[8:11], v[224:227], v[148:151]
	v_mfma_f32_16x16x32_bf16 v[0:3], v[8:11], v[232:235], v[0:3]
	v_mfma_f32_16x16x32_bf16 v[28:31], v[12:15], v[228:231], v[24:27]
	v_mfma_f32_16x16x32_bf16 v[24:27], v[16:19], v[224:227], v[152:155]
	v_mfma_f32_16x16x32_bf16 v[12:15], v[12:15], v[236:239], v[0:3]
	v_mfma_f32_16x16x32_bf16 v[0:3], v[16:19], v[232:235], v[4:7]
	v_mfma_f32_16x16x32_bf16 v[24:27], v[20:23], v[228:231], v[24:27]
	v_mfma_f32_16x16x32_bf16 v[8:11], v[20:23], v[236:239], v[0:3]
	v_mfma_f32_16x16x32_bf16 v[0:3], v[192:195], v[32:35], v[156:159]
	v_mfma_f32_16x16x32_bf16 v[52:55], v[196:199], v[36:39], v[0:3]
	v_mfma_f32_16x16x32_bf16 v[0:3], v[200:203], v[32:35], v[160:163]
	v_mfma_f32_16x16x32_bf16 v[48:51], v[212:215], v[36:39], v[0:3]
	v_mfma_f32_16x16x32_bf16 v[0:3], v[192:195], v[216:219], v[164:167]
	v_mfma_f32_16x16x32_bf16 v[36:39], v[196:199], v[220:223], v[0:3]
	v_mfma_f32_16x16x32_bf16 v[0:3], v[200:203], v[216:219], v[168:171]
	v_mfma_f32_16x16x32_bf16 v[32:35], v[212:215], v[220:223], v[0:3]
	v_mfma_f32_16x16x32_bf16 v[0:3], v[192:195], v[224:227], v[172:175]
	v_mfma_f32_16x16x32_bf16 v[20:23], v[196:199], v[228:231], v[0:3]
	v_mfma_f32_16x16x32_bf16 v[0:3], v[200:203], v[224:227], v[176:179]
	v_mfma_f32_16x16x32_bf16 v[16:19], v[212:215], v[228:231], v[0:3]
	v_mfma_f32_16x16x32_bf16 v[0:3], v[192:195], v[232:235], v[180:183]
	v_mfma_f32_16x16x32_bf16 v[4:7], v[196:199], v[236:239], v[0:3]
	v_mfma_f32_16x16x32_bf16 v[0:3], v[200:203], v[232:235], v[188:191]
	v_mfma_f32_16x16x32_bf16 v[0:3], v[212:215], v[236:239], v[0:3]
	s_barrier
	s_andn2_b64 vcc, exec, s[14:15]
	s_cbranch_vccnz .LBB0_543
	s_barrier

; __device__ __forceinline__ int lane_id() { int l; asm volatile("v_mbcnt_lo_u32_b32 %0, -1, 0\n\tv_mbcnt_hi_u32_b32 %0, -1, %0" : "=v"(l)); return l; }
;     __device__ __forceinline__ bool next(int i, UnitG& u) const { if (!P.next(i, u)) return false; u.O = O + ((size_t)u.x0 * 256 * 2048 + (size_t)u.x1 * 256) * 2; u.ldo = 2048; u.kind = 0; return true; }
; template <class Epi, class Sched>
; __device__ __forceinline__ void gemm_phase(PG8_LAS unsigned char* lds, const Sched& S, const Epi& E, int tid_in) {
;     ...
;         int aoff, boff; { const int l3 = lane_id(), fr3 = l3 & 15, fq3 = l3 >> 4; aoff = lds_byte(wr * 64 + fr3, fq3 * 8); boff = lds_byte(wc * 32 + fr3, fq3 * 8); }
;         const bool has_next = S.next(ui + 1, nxt);
;         const char* nA = has_next ? nxt.A : cA; const char* nB = has_next ? nxt.B : cB;
;         const int nlda = has_next ? nxt.lda : cur.lda, nldb = has_next ? nxt.ldb : cur.ldb;
;         unsigned nvA, nvB; { int r2, c2; stage_rc((wid * 64 + lane_id()) * 16, r2, c2); const int rb2 = Epi::PERM ? ((r2 & ~31) + perm32(r2 & 31)) : r2;
;             nvA = (unsigned)(r2 * nlda + c2) * 2u; nvB = (unsigned)(rb2 * nldb + c2) * 2u; }
;         const unsigned nqA = (unsigned)nlda * 128u, nqB = (unsigned)nldb * 128u;
;         const int nt = cur.K / BK;
.LBB0_1273:
	v_and_b32_e32 v1, 15, v0
	v_or_b32_e32 v2, s77, v1
	v_lshlrev_b32_e32 v3, 6, v2
	v_and_b32_e32 v4, 48, v0
	s_movk_i32 s5, 0x3c0
	v_lshlrev_b32_e32 v5, 4, v0
	v_and_or_b32 v3, v3, s5, v4
	v_and_b32_e32 v5, 0xfffffc00, v5
	v_readlane_b32 s5, v255, 5
	v_lshlrev_b32_e32 v2, 2, v2
	v_and_b32_e32 v2, 32, v2
	v_add_u32_e32 v6, s5, v5
	v_readlane_b32 s5, v255, 7
	v_lshlrev_b32_e32 v0, 2, v0
	s_waitcnt vmcnt(4)
	v_bitop3_b32 v32, v3, v6, v2 bitop3:0xde
	v_lshl_or_b32 v1, v1, 6, v4
	v_add_u32_e32 v2, s5, v5
	v_and_b32_e32 v0, 32, v0
	v_bitop3_b32 v137, v1, v2, v0 bitop3:0xde
	v_mbcnt_lo_u32_b32 v0, -1, 0
	v_mbcnt_hi_u32_b32 v0, -1, v0
	v_readlane_b32 s5, v255, 9
	s_add_i32 s93, 0, 0x10000
	s_add_i32 s8, 0, 0x14000
	v_add_u32_e32 v0, s5, v0
	v_ashrrev_i32_e32 v2, 31, v0
	v_lshrrev_b32_e32 v2, 26, v2
	v_lshlrev_b32_e32 v1, 4, v0
	v_add_u32_e32 v2, v0, v2
	v_bfe_i32 v0, v0, 27, 1
	v_lshrrev_b32_e32 v0, 22, v0
	v_add_u32_e32 v0, v1, v0
	v_and_b32_e32 v0, 0xfffffc00, v0
	v_sub_u32_e32 v0, v1, v0
	v_lshrrev_b32_e32 v1, 4, v0
	v_bitop3_b32 v0, v1, v0, 32 bitop3:0x6c
	v_ashrrev_i32_e32 v3, 31, v0
	v_lshrrev_b32_e32 v3, 26, v3
	v_ashrrev_i32_e32 v2, 6, v2
	v_add_u32_e32 v3, v0, v3
	v_lshlrev_b32_e32 v1, 3, v2
	v_ashrrev_i32_e32 v4, 6, v3
	v_and_b32_e32 v3, 0xc0, v3
	v_and_b32_e32 v1, -16, v1
	v_lshlrev_b32_e32 v2, 5, v2
	v_sub_u32_e32 v0, v0, v3
	v_add_u32_e32 v1, v4, v1
	v_and_b32_e32 v2, 32, v2
	v_ashrrev_i16_sdwa v0, v205, sext(v0) dst_sel:DWORD dst_unused:UNUSED_PAD src0_sel:DWORD src1_sel:BYTE_0
	v_add_u32_sdwa v33, v2, sext(v0) dst_sel:DWORD dst_unused:UNUSED_PAD src0_sel:DWORD src1_sel:WORD_0
	v_lshlrev_b32_e32 v0, 1, v1
	v_lshrrev_b32_e32 v2, 2, v1
	v_and_b32_e32 v3, 3, v4
	s_mov_b32 s5, 0x7fffffe0
	v_and_b32_e32 v0, 24, v0
	v_and_b32_e32 v2, 4, v2
	v_and_or_b32 v3, v1, s5, v3
	v_or3_b32 v0, v3, v2, v0
	v_mul_lo_u32 v1, v1, s54
	v_add_u32_e32 v142, s93, v137
	v_add_u32_e32 v143, s8, v137
	v_add_lshl_u32 v136, v33, v1, 1
	v_mul_lo_u32 v34, v0, s54
	ds_read_b128 v[0:3], v142
	ds_read_b128 v[4:7], v142 offset:1024
	ds_read_b128 v[8:11], v142 offset:2048
	ds_read_b128 v[12:15], v142 offset:3072
	ds_read_b128 v[16:19], v143
	ds_read_b128 v[20:23], v143 offset:1024
	ds_read_b128 v[24:27], v143 offset:2048
	ds_read_b128 v[28:31], v143 offset:3072
	s_mov_b32 s86, 4
	s_lshl_b32 s34, s54, 7
	s_lshr_b32 s87, s71, 6
	s_lshl_b32 s82, s6, 1
	s_lshl_b32 s44, s54, 7
	v_add_lshl_u32 v138, v34, v33, 1
	s_add_u32 s10, s46, s82
	s_addc_u32 s11, s47, 0
	v_lshl_add_u64 v[124:125], s[10:11], 0, v[184:185]
	s_add_i32 s72, s14, 0xc000
	s_mov_b32 s7, s83
	v_add_u32_e32 v144, 0, v32
	v_lshl_add_u64 v[64:65], v[124:125], 0, s[84:85]
	s_mov_b32 m0, s72
	v_lshl_add_u64 v[126:127], v[124:125], 0, s[6:7]
	s_add_i32 s92, s14, 0xe000
	ds_read_b128 v[32:35], v144
	ds_read_b128 v[36:39], v144 offset:1024
	ds_read_b128 v[40:43], v144 offset:2048
	ds_read_b128 v[44:47], v144 offset:3072
	ds_read_b128 v[48:51], v144 offset:4096
	ds_read_b128 v[52:55], v144 offset:5120
	ds_read_b128 v[56:59], v144 offset:6144
	ds_read_b128 v[60:63], v144 offset:7168
	global_load_lds_dwordx4 v[64:65], off
	v_lshl_add_u64 v[64:65], v[126:127], 0, s[84:85]
	s_mov_b32 m0, s92
	s_nop 0
	global_load_lds_dwordx4 v[64:65], off
	s_waitcnt vmcnt(24)
	s_waitcnt lgkmcnt(0)
	s_barrier
	s_waitcnt lgkmcnt(0)
	v_mfma_f32_16x16x32_bf16 v[64:67], v[0:3], v[32:35], 0
	v_mfma_f32_16x16x32_bf16 v[68:71], v[8:11], v[32:35], 0
	v_mfma_f32_16x16x32_bf16 v[72:75], v[0:3], v[40:43], 0
	v_mfma_f32_16x16x32_bf16 v[76:79], v[8:11], v[40:43], 0
	v_mfma_f32_16x16x32_bf16 v[80:83], v[0:3], v[48:51], 0
	v_mfma_f32_16x16x32_bf16 v[84:87], v[8:11], v[48:51], 0
	v_mfma_f32_16x16x32_bf16 v[88:91], v[0:3], v[56:59], 0
	v_mfma_f32_16x16x32_bf16 v[92:95], v[8:11], v[56:59], 0
	v_mfma_f32_16x16x32_bf16 v[64:67], v[4:7], v[36:39], v[64:67]
	v_mfma_f32_16x16x32_bf16 v[68:71], v[12:15], v[36:39], v[68:71]
	v_mfma_f32_16x16x32_bf16 v[72:75], v[4:7], v[44:47], v[72:75]
	v_mfma_f32_16x16x32_bf16 v[76:79], v[12:15], v[44:47], v[76:79]
	v_mfma_f32_16x16x32_bf16 v[80:83], v[4:7], v[52:55], v[80:83]
	v_mfma_f32_16x16x32_bf16 v[84:87], v[12:15], v[52:55], v[84:87]
	v_mfma_f32_16x16x32_bf16 v[88:91], v[4:7], v[60:63], v[88:91]
	v_mfma_f32_16x16x32_bf16 v[92:95], v[12:15], v[60:63], v[92:95]
	v_mfma_f32_16x16x32_bf16 v[96:99], v[16:19], v[32:35], 0
	v_mfma_f32_16x16x32_bf16 v[32:35], v[24:27], v[32:35], 0
	v_mfma_f32_16x16x32_bf16 v[130:133], v[20:23], v[36:39], v[96:99]
	v_mfma_f32_16x16x32_bf16 v[32:35], v[28:31], v[36:39], v[32:35]
	v_mfma_f32_16x16x32_bf16 v[36:39], v[16:19], v[40:43], 0
	v_mfma_f32_16x16x32_bf16 v[40:43], v[24:27], v[40:43], 0
	v_mfma_f32_16x16x32_bf16 v[36:39], v[20:23], v[44:47], v[36:39]
	v_mfma_f32_16x16x32_bf16 v[40:43], v[28:31], v[44:47], v[40:43]
	v_mfma_f32_16x16x32_bf16 v[44:47], v[16:19], v[48:51], 0
	v_mfma_f32_16x16x32_bf16 v[48:51], v[24:27], v[48:51], 0
	v_mfma_f32_16x16x32_bf16 v[44:47], v[20:23], v[52:55], v[44:47]
	v_mfma_f32_16x16x32_bf16 v[52:55], v[28:31], v[52:55], v[48:51]
	v_mfma_f32_16x16x32_bf16 v[48:51], v[16:19], v[56:59], 0
	v_mfma_f32_16x16x32_bf16 v[148:151], v[20:23], v[60:63], v[48:51]
	v_mfma_f32_16x16x32_bf16 v[48:51], v[24:27], v[56:59], 0
	v_mfma_f32_16x16x32_bf16 v[56:59], v[28:31], v[60:63], v[48:51]
	s_barrier
	s_add_i32 s93, s93, s15
	v_mov_b32_e32 v129, v185
	s_add_i32 s10, s93, 0x2000
	s_lshl_b32 s50, s4, 1
	v_lshl_add_u64 v[134:135], s[48:49], 0, v[128:129]
	s_mov_b64 s[52:53], 0x100
	s_mov_b32 s5, s83
	s_add_u32 s16, s48, s50
	v_lshl_add_u64 v[120:121], v[134:135], 0, s[52:53]
	s_mov_b32 m0, s93
	v_lshl_add_u64 v[140:141], v[134:135], 0, s[4:5]
	s_addc_u32 s17, s49, 0
	ds_read_b128 v[48:51], v144 offset:16384
	ds_read_b128 v[60:63], v144 offset:17408
	ds_read_b128 v[96:99], v144 offset:18432
	ds_read_b128 v[100:103], v144 offset:19456
	ds_read_b128 v[104:107], v144 offset:20480
	ds_read_b128 v[108:111], v144 offset:21504
	ds_read_b128 v[112:115], v144 offset:22528
	ds_read_b128 v[116:119], v144 offset:23552
	global_load_lds_dwordx4 v[120:121], off
	v_lshl_add_u64 v[120:121], v[140:141], 0, s[52:53]
	s_mov_b32 m0, s10
	v_lshl_add_u64 v[186:187], s[16:17], 0, v[128:129]
	s_add_i32 s11, s8, s15
	global_load_lds_dwordx4 v[120:121], off
	v_lshl_add_u64 v[120:121], v[186:187], 0, s[52:53]
	s_mov_b32 m0, s11
	v_lshl_add_u64 v[206:207], v[186:187], 0, s[4:5]
	s_add_i32 s8, s11, 0x2000
	global_load_lds_dwordx4 v[120:121], off
	v_lshl_add_u64 v[120:121], v[206:207], 0, s[52:53]
	s_mov_b32 m0, s8
	v_lshl_add_u64 v[210:211], s[46:47], 0, v[184:185]
	global_load_lds_dwordx4 v[120:121], off
	v_lshl_add_u64 v[120:121], v[210:211], 0, s[52:53]
	s_mov_b32 m0, s14
	v_lshl_add_u64 v[252:253], v[210:211], 0, s[6:7]
	global_load_lds_dwordx4 v[120:121], off
	v_lshl_add_u64 v[120:121], v[252:253], 0, s[52:53]
	s_mov_b32 m0, s73
	s_mov_b32 s51, s83
	global_load_lds_dwordx4 v[120:121], off
	s_waitcnt vmcnt(24)
	s_waitcnt lgkmcnt(0)
	s_barrier
	s_waitcnt lgkmcnt(0)
	v_mfma_f32_16x16x32_bf16 v[120:123], v[0:3], v[48:51], 0
	v_mfma_f32_16x16x32_bf16 v[152:155], v[4:7], v[60:63], v[120:123]
	v_mfma_f32_16x16x32_bf16 v[120:123], v[8:11], v[48:51], 0
	v_mfma_f32_16x16x32_bf16 v[156:159], v[12:15], v[60:63], v[120:123]
	v_mfma_f32_16x16x32_bf16 v[120:123], v[0:3], v[96:99], 0
	v_mfma_f32_16x16x32_bf16 v[160:163], v[4:7], v[100:103], v[120:123]
	v_mfma_f32_16x16x32_bf16 v[120:123], v[8:11], v[96:99], 0
	v_mfma_f32_16x16x32_bf16 v[164:167], v[12:15], v[100:103], v[120:123]
	v_mfma_f32_16x16x32_bf16 v[120:123], v[0:3], v[104:107], 0
	v_mfma_f32_16x16x32_bf16 v[0:3], v[0:3], v[112:115], 0
	v_mfma_f32_16x16x32_bf16 v[168:171], v[4:7], v[108:111], v[120:123]
	v_mfma_f32_16x16x32_bf16 v[0:3], v[4:7], v[116:119], v[0:3]
	v_mfma_f32_16x16x32_bf16 v[4:7], v[8:11], v[112:115], 0
	v_mfma_f32_16x16x32_bf16 v[120:123], v[8:11], v[104:107], 0
	v_mfma_f32_16x16x32_bf16 v[4:7], v[12:15], v[116:119], v[4:7]
	v_mfma_f32_16x16x32_bf16 v[172:175], v[12:15], v[108:111], v[120:123]
	v_mfma_f32_16x16x32_bf16 v[8:11], v[16:19], v[48:51], 0
	v_mfma_f32_16x16x32_bf16 v[12:15], v[24:27], v[48:51], 0
	v_mfma_f32_16x16x32_bf16 v[48:51], v[16:19], v[96:99], 0
	v_mfma_f32_16x16x32_bf16 v[176:179], v[20:23], v[100:103], v[48:51]
	v_mfma_f32_16x16x32_bf16 v[48:51], v[24:27], v[96:99], 0
	v_mfma_f32_16x16x32_bf16 v[180:183], v[28:31], v[100:103], v[48:51]
	v_mfma_f32_16x16x32_bf16 v[48:51], v[16:19], v[104:107], 0
	v_mfma_f32_16x16x32_bf16 v[16:19], v[16:19], v[112:115], 0
	v_mfma_f32_16x16x32_bf16 v[8:11], v[20:23], v[60:63], v[8:11]
	v_mfma_f32_16x16x32_bf16 v[12:15], v[28:31], v[60:63], v[12:15]
	v_mfma_f32_16x16x32_bf16 v[188:191], v[20:23], v[108:111], v[48:51]
	v_mfma_f32_16x16x32_bf16 v[48:51], v[24:27], v[104:107], 0
	v_mfma_f32_16x16x32_bf16 v[196:199], v[20:23], v[116:119], v[16:19]
	v_mfma_f32_16x16x32_bf16 v[16:19], v[24:27], v[112:115], 0
	v_mfma_f32_16x16x32_bf16 v[192:195], v[28:31], v[108:111], v[48:51]
	v_mfma_f32_16x16x32_bf16 v[200:203], v[28:31], v[116:119], v[16:19]
	s_barrier
	s_add_i32 s16, 0, 0x18000
	s_add_i32 s24, 0, 0x1c000
	v_add_u32_e32 v145, s16, v137
	v_add_u32_e32 v146, s24, v137
	ds_read_b128 v[16:19], v145
	ds_read_b128 v[20:23], v145 offset:1024
	ds_read_b128 v[24:27], v145 offset:2048
	ds_read_b128 v[28:31], v145 offset:3072
	ds_read_b128 v[212:215], v146
	ds_read_b128 v[216:219], v146 offset:1024
	ds_read_b128 v[220:223], v146 offset:2048
	ds_read_b128 v[224:227], v146 offset:3072
	s_mov_b32 m0, s74
	v_lshl_add_u64 v[96:97], v[124:125], 0, s[52:53]
	ds_read_b128 v[48:51], v144 offset:32768
	ds_read_b128 v[60:63], v144 offset:33792
	ds_read_b128 v[228:231], v144 offset:34816
	ds_read_b128 v[232:235], v144 offset:35840
	ds_read_b128 v[236:239], v144 offset:36864
	ds_read_b128 v[240:243], v144 offset:37888
	ds_read_b128 v[244:247], v144 offset:38912
	ds_read_b128 v[248:251], v144 offset:39936
	global_load_lds_dwordx4 v[96:97], off
	v_lshl_add_u64 v[96:97], v[126:127], 0, s[52:53]
	s_mov_b32 m0, s75
	s_nop 0
	global_load_lds_dwordx4 v[96:97], off
	s_waitcnt vmcnt(8)
	s_waitcnt lgkmcnt(0)
	s_barrier
; #define PG8_WAIT_V(n) asm volatile("s_waitcnt vmcnt(" #n ")" ::: "memory")
; #define PG8_WAIT_VP() asm volatile("s_waitcnt vmcnt(%0)" :: "n"(8 + Epi::NST) : "memory")
; template <class Epi, class Sched>
; __device__ __forceinline__ void gemm_phase(PG8_LAS unsigned char* lds, const Sched& S, const Epi& E, int tid_in) {
;     ...
;         { const int t = 0; PG8_KITER(PG8_WAIT_VP()); }
;         for (int t = 2; t < nt; t += 2) PG8_KITER(PG8_WAIT_V(8));
	s_waitcnt lgkmcnt(0)
	v_mfma_f32_16x16x32_bf16 v[64:67], v[16:19], v[48:51], v[64:67]
	v_mfma_f32_16x16x32_bf16 v[120:123], v[20:23], v[60:63], v[64:67]
	v_mfma_f32_16x16x32_bf16 v[64:67], v[24:27], v[48:51], v[68:71]
	v_mfma_f32_16x16x32_bf16 v[124:127], v[28:31], v[60:63], v[64:67]
	v_mfma_f32_16x16x32_bf16 v[64:67], v[16:19], v[228:231], v[72:75]
	v_mfma_f32_16x16x32_bf16 v[112:115], v[20:23], v[232:235], v[64:67]
	v_mfma_f32_16x16x32_bf16 v[64:67], v[24:27], v[228:231], v[76:79]
	v_mfma_f32_16x16x32_bf16 v[116:119], v[28:31], v[232:235], v[64:67]
	v_mfma_f32_16x16x32_bf16 v[64:67], v[16:19], v[236:239], v[80:83]
	v_mfma_f32_16x16x32_bf16 v[104:107], v[20:23], v[240:243], v[64:67]
	v_mfma_f32_16x16x32_bf16 v[64:67], v[24:27], v[236:239], v[84:87]
	v_mfma_f32_16x16x32_bf16 v[108:111], v[28:31], v[240:243], v[64:67]
	v_mfma_f32_16x16x32_bf16 v[64:67], v[16:19], v[244:247], v[88:91]
	v_mfma_f32_16x16x32_bf16 v[96:99], v[20:23], v[248:251], v[64:67]
	v_mfma_f32_16x16x32_bf16 v[64:67], v[24:27], v[244:247], v[92:95]
	v_mfma_f32_16x16x32_bf16 v[100:103], v[28:31], v[248:251], v[64:67]
	v_mfma_f32_16x16x32_bf16 v[32:35], v[220:223], v[48:51], v[32:35]
	v_mfma_f32_16x16x32_bf16 v[64:67], v[212:215], v[48:51], v[130:133]
	v_mfma_f32_16x16x32_bf16 v[84:87], v[224:227], v[60:63], v[32:35]
	v_mfma_f32_16x16x32_bf16 v[32:35], v[212:215], v[228:231], v[36:39]
	v_mfma_f32_16x16x32_bf16 v[80:83], v[216:219], v[60:63], v[64:67]
	v_mfma_f32_16x16x32_bf16 v[64:67], v[216:219], v[232:235], v[32:35]
	v_mfma_f32_16x16x32_bf16 v[32:35], v[220:223], v[228:231], v[40:43]
	v_mfma_f32_16x16x32_bf16 v[68:71], v[224:227], v[232:235], v[32:35]
	v_mfma_f32_16x16x32_bf16 v[32:35], v[212:215], v[236:239], v[44:47]
	v_mfma_f32_16x16x32_bf16 v[48:51], v[216:219], v[240:243], v[32:35]
	v_mfma_f32_16x16x32_bf16 v[32:35], v[220:223], v[236:239], v[52:55]
	v_mfma_f32_16x16x32_bf16 v[52:55], v[224:227], v[240:243], v[32:35]
	v_mfma_f32_16x16x32_bf16 v[32:35], v[212:215], v[244:247], v[148:151]
	v_mfma_f32_16x16x32_bf16 v[36:39], v[220:223], v[244:247], v[56:59]
	v_mfma_f32_16x16x32_bf16 v[32:35], v[216:219], v[248:251], v[32:35]
	v_mfma_f32_16x16x32_bf16 v[36:39], v[224:227], v[248:251], v[36:39]
	s_barrier
	s_mov_b64 s[52:53], 0x180
	s_add_i32 s16, s16, s15
	v_lshl_add_u64 v[40:41], v[134:135], 0, s[52:53]
	s_mov_b32 m0, s16
	s_add_i32 s17, s16, 0x2000
	ds_read_b128 v[130:133], v144 offset:49152
	ds_read_b128 v[148:151], v144 offset:50176
	ds_read_b128 v[228:231], v144 offset:51200
	ds_read_b128 v[232:235], v144 offset:52224
	ds_read_b128 v[236:239], v144 offset:53248
	ds_read_b128 v[240:243], v144 offset:54272
	ds_read_b128 v[244:247], v144 offset:55296
	ds_read_b128 v[248:251], v144 offset:56320
	global_load_lds_dwordx4 v[40:41], off
	v_lshl_add_u64 v[40:41], v[140:141], 0, s[52:53]
	s_mov_b32 m0, s17
	s_add_i32 s24, s24, s15
	global_load_lds_dwordx4 v[40:41], off
	v_lshl_add_u64 v[40:41], v[186:187], 0, s[52:53]
	s_mov_b32 m0, s24
	s_add_i32 s25, s24, 0x2000
	global_load_lds_dwordx4 v[40:41], off
	v_lshl_add_u64 v[40:41], v[206:207], 0, s[52:53]
	s_mov_b32 m0, s25
	s_nop 0
	global_load_lds_dwordx4 v[40:41], off
	v_lshl_add_u64 v[40:41], v[210:211], 0, s[52:53]
	s_mov_b32 m0, s13
	s_nop 0
	global_load_lds_dwordx4 v[40:41], off
	v_lshl_add_u64 v[40:41], v[252:253], 0, s[52:53]
	s_mov_b32 m0, s76
	v_mov_b32_e32 v252, 0x3a27c5ac
	global_load_lds_dwordx4 v[40:41], off
	s_waitcnt vmcnt(8)
	s_waitcnt lgkmcnt(0)
	s_barrier
	s_waitcnt lgkmcnt(0)
	v_mfma_f32_16x16x32_bf16 v[40:43], v[16:19], v[130:133], v[152:155]
	v_mfma_f32_16x16x32_bf16 v[88:91], v[20:23], v[148:151], v[40:43]
	v_mfma_f32_16x16x32_bf16 v[40:43], v[24:27], v[130:133], v[156:159]
	v_mfma_f32_16x16x32_bf16 v[92:95], v[28:31], v[148:151], v[40:43]
	v_mfma_f32_16x16x32_bf16 v[40:43], v[16:19], v[228:231], v[160:163]
	v_mfma_f32_16x16x32_bf16 v[72:75], v[20:23], v[232:235], v[40:43]
	v_mfma_f32_16x16x32_bf16 v[40:43], v[24:27], v[228:231], v[164:167]
	v_mfma_f32_16x16x32_bf16 v[76:79], v[28:31], v[232:235], v[40:43]
	v_mfma_f32_16x16x32_bf16 v[40:43], v[16:19], v[236:239], v[168:171]
	v_mfma_f32_16x16x32_bf16 v[56:59], v[20:23], v[240:243], v[40:43]
	v_mfma_f32_16x16x32_bf16 v[40:43], v[24:27], v[236:239], v[172:175]
	v_mfma_f32_16x16x32_bf16 v[0:3], v[16:19], v[244:247], v[0:3]
	v_mfma_f32_16x16x32_bf16 v[60:63], v[28:31], v[240:243], v[40:43]
	v_mfma_f32_16x16x32_bf16 v[40:43], v[20:23], v[248:251], v[0:3]
	v_mfma_f32_16x16x32_bf16 v[0:3], v[24:27], v[244:247], v[4:7]
	v_mfma_f32_16x16x32_bf16 v[44:47], v[28:31], v[248:251], v[0:3]
	v_mfma_f32_16x16x32_bf16 v[0:3], v[212:215], v[130:133], v[8:11]
	v_mfma_f32_16x16x32_bf16 v[24:27], v[216:219], v[148:151], v[0:3]
	v_mfma_f32_16x16x32_bf16 v[0:3], v[220:223], v[130:133], v[12:15]
	v_mfma_f32_16x16x32_bf16 v[28:31], v[224:227], v[148:151], v[0:3]
	v_mfma_f32_16x16x32_bf16 v[0:3], v[212:215], v[228:231], v[176:179]
	v_mfma_f32_16x16x32_bf16 v[16:19], v[216:219], v[232:235], v[0:3]
	v_mfma_f32_16x16x32_bf16 v[0:3], v[220:223], v[228:231], v[180:183]
	v_mfma_f32_16x16x32_bf16 v[20:23], v[224:227], v[232:235], v[0:3]
	v_mfma_f32_16x16x32_bf16 v[0:3], v[212:215], v[236:239], v[188:191]
	v_mfma_f32_16x16x32_bf16 v[8:11], v[216:219], v[240:243], v[0:3]
	v_mfma_f32_16x16x32_bf16 v[0:3], v[220:223], v[236:239], v[192:195]
	v_mfma_f32_16x16x32_bf16 v[12:15], v[224:227], v[240:243], v[0:3]
	v_mfma_f32_16x16x32_bf16 v[0:3], v[212:215], v[244:247], v[196:199]
	v_mfma_f32_16x16x32_bf16 v[4:7], v[220:223], v[244:247], v[200:203]
	v_mfma_f32_16x16x32_bf16 v[0:3], v[216:219], v[248:251], v[0:3]
	v_mfma_f32_16x16x32_bf16 v[4:7], v[224:227], v[248:251], v[4:7]
	s_barrier
	s_lshl_b32 s52, s54, 8
	s_lshl_b32 s54, s54, 8
	s_add_u32 s46, s46, 0x180
	s_addc_u32 s47, s47, 0
	s_add_u32 s48, s48, 0x200
	v_mov_b32_e32 v137, v185
	s_mov_b32 s35, s83
	s_mov_b32 s53, s83
	v_mov_b32_e32 v139, v185
	s_mov_b32 s45, s83
	s_mov_b32 s55, s83
	s_addc_u32 s49, s49, 0
	v_lshl_add_u64 v[130:131], s[82:83], 0, v[184:185]
	v_mad_u64_u32 v[132:133], s[56:57], s6, 3, v[184:185]

; __device__ __forceinline__ int lane_id() { int l; asm volatile("v_mbcnt_lo_u32_b32 %0, -1, 0\n\tv_mbcnt_hi_u32_b32 %0, -1, %0" : "=v"(l)); return l; }
;     __device__ __forceinline__ bool next(int i, UnitG& u) const { if (!P.next(i, u)) return false; u.O = O + ((size_t)u.x0 * 256 * 2048 + (size_t)u.x1 * 256) * 2; u.ldo = 2048; u.kind = 0; return true; }
; template <class Epi, class Sched>
; __device__ __forceinline__ void gemm_phase(PG8_LAS unsigned char* lds, const Sched& S, const Epi& E, int tid_in) {
;     ...
;         int aoff, boff; { const int l3 = lane_id(), fr3 = l3 & 15, fq3 = l3 >> 4; aoff = lds_byte(wr * 64 + fr3, fq3 * 8); boff = lds_byte(wc * 32 + fr3, fq3 * 8); }
;         const bool has_next = S.next(ui + 1, nxt);
;         const char* nA = has_next ? nxt.A : cA; const char* nB = has_next ? nxt.B : cB;
;         const int nlda = has_next ? nxt.lda : cur.lda, nldb = has_next ? nxt.ldb : cur.ldb;
;         unsigned nvA, nvB; { int r2, c2; stage_rc((wid * 64 + lane_id()) * 16, r2, c2); const int rb2 = Epi::PERM ? ((r2 & ~31) + perm32(r2 & 31)) : r2;
;             nvA = (unsigned)(r2 * nlda + c2) * 2u; nvB = (unsigned)(rb2 * nldb + c2) * 2u; }
;         const unsigned nqA = (unsigned)nlda * 128u, nqB = (unsigned)nldb * 128u;
;         const int nt = cur.K / BK;
.LBB0_1445:
	v_and_b32_e32 v1, 15, v0
	v_or_b32_e32 v2, s46, v1
	v_ashrrev_i32_e32 v3, 6, v0
	v_lshlrev_b32_e32 v4, 6, v2
	v_and_b32_e32 v5, 48, v0
	s_movk_i32 s53, 0x3c0
	v_lshlrev_b32_e32 v2, 2, v2
	v_and_or_b32 v4, v4, s53, v5
	v_lshl_add_u32 v6, v3, 10, s47
	v_and_b32_e32 v2, 32, v2
	v_lshlrev_b32_e32 v0, 2, v0
	s_waitcnt vmcnt(4)
	v_bitop3_b32 v32, v4, v6, v2 bitop3:0xde
	v_lshl_or_b32 v1, v1, 6, v5
	v_add_lshl_u32 v2, v3, s49, 10
	v_and_b32_e32 v0, 32, v0
	v_bitop3_b32 v119, v1, v2, v0 bitop3:0xde
	v_mbcnt_lo_u32_b32 v0, -1, 0
	v_mbcnt_hi_u32_b32 v0, -1, v0
	s_mov_b32 s53, 0xfffe0
	v_add_u32_e32 v0, s50, v0
	v_ashrrev_i32_e32 v2, 31, v0
	v_lshrrev_b32_e32 v2, 26, v2
	v_lshlrev_b32_e32 v1, 4, v0
	v_add_u32_e32 v2, v0, v2
	v_bfe_i32 v0, v0, 27, 1
	v_lshrrev_b32_e32 v0, 22, v0
	v_add_u32_e32 v0, v1, v0
	v_and_b32_e32 v0, 0xfffffc00, v0
	v_sub_u32_e32 v0, v1, v0
	v_lshrrev_b32_e32 v1, 4, v0
	v_bitop3_b32 v0, v1, v0, 32 bitop3:0x6c
	v_ashrrev_i32_e32 v3, 31, v0
	v_lshrrev_b32_e32 v3, 26, v3
	v_ashrrev_i32_e32 v2, 6, v2
	v_add_u32_e32 v3, v0, v3
	v_lshlrev_b32_e32 v1, 3, v2
	v_ashrrev_i32_e32 v4, 6, v3
	v_and_b32_e32 v3, 0xc0, v3
	v_and_b32_e32 v1, -16, v1
	v_sub_u32_e32 v0, v0, v3
	v_add_u32_e32 v1, v4, v1
	v_lshlrev_b32_e32 v2, 5, v2
	v_ashrrev_i16_sdwa v0, v205, sext(v0) dst_sel:DWORD dst_unused:UNUSED_PAD src0_sel:DWORD src1_sel:BYTE_0
	v_and_b32_e32 v2, 32, v2
	v_bfe_i32 v0, v0, 0, 16
	v_lshlrev_b32_e32 v3, 1, v1
	v_lshrrev_b32_e32 v5, 2, v1
	v_and_b32_e32 v4, 3, v4
	s_add_i32 s55, 0, 0x10000
	s_add_i32 s57, 0, 0x14000
	v_and_b32_e32 v3, 24, v3
	v_and_b32_e32 v5, 4, v5
	v_and_or_b32 v4, v1, s53, v4
	v_add_lshl_u32 v34, v2, v0, 1
	v_add_u32_e32 v116, s55, v119
	v_add_u32_e32 v117, s57, v119
	v_or3_b32 v33, v4, v5, v3
	v_lshl_add_u32 v186, v1, 12, v34
	ds_read_b128 v[0:3], v116
	ds_read_b128 v[4:7], v116 offset:1024
	ds_read_b128 v[8:11], v116 offset:2048
	ds_read_b128 v[12:15], v116 offset:3072
	ds_read_b128 v[16:19], v117
	ds_read_b128 v[20:23], v117 offset:1024
	ds_read_b128 v[24:27], v117 offset:2048
	ds_read_b128 v[28:31], v117 offset:3072
	v_lshl_add_u32 v211, v33, 12, v34
	v_mov_b32_e32 v115, v185
	v_lshl_add_u64 v[206:207], s[20:21], 0, v[114:115]
	s_add_i32 s53, s7, 0xc000
	v_add_u32_e32 v118, 0, v32
	v_lshl_add_u64 v[64:65], v[206:207], 0, s[80:81]
	s_mov_b32 m0, s53
	s_add_i32 s54, s7, 0xe000
	ds_read_b128 v[32:35], v118
	ds_read_b128 v[36:39], v118 offset:1024
	ds_read_b128 v[40:43], v118 offset:2048
	ds_read_b128 v[44:47], v118 offset:3072
	ds_read_b128 v[48:51], v118 offset:4096
	ds_read_b128 v[52:55], v118 offset:5120
	ds_read_b128 v[56:59], v118 offset:6144
	ds_read_b128 v[60:63], v118 offset:7168
	global_load_lds_dwordx4 v[64:65], off
	v_lshl_add_u64 v[64:65], v[206:207], 0, s[78:79]
	s_mov_b32 m0, s54
	s_nop 0
	global_load_lds_dwordx4 v[64:65], off
	s_waitcnt vmcnt(24)
	s_waitcnt lgkmcnt(0)
	s_barrier
	s_waitcnt lgkmcnt(0)
	v_mfma_f32_16x16x32_bf16 v[88:91], v[0:3], v[56:59], 0
	v_mfma_f32_16x16x32_bf16 v[64:67], v[0:3], v[32:35], 0
	v_mfma_f32_16x16x32_bf16 v[68:71], v[8:11], v[32:35], 0
	v_mfma_f32_16x16x32_bf16 v[72:75], v[0:3], v[40:43], 0
	v_mfma_f32_16x16x32_bf16 v[76:79], v[8:11], v[40:43], 0
	v_mfma_f32_16x16x32_bf16 v[80:83], v[0:3], v[48:51], 0
	v_mfma_f32_16x16x32_bf16 v[84:87], v[8:11], v[48:51], 0
	v_mfma_f32_16x16x32_bf16 v[96:99], v[4:7], v[60:63], v[88:91]
	v_mfma_f32_16x16x32_bf16 v[88:91], v[8:11], v[56:59], 0
	v_mfma_f32_16x16x32_bf16 v[64:67], v[4:7], v[36:39], v[64:67]
	v_mfma_f32_16x16x32_bf16 v[68:71], v[12:15], v[36:39], v[68:71]
	v_mfma_f32_16x16x32_bf16 v[72:75], v[4:7], v[44:47], v[72:75]
	v_mfma_f32_16x16x32_bf16 v[76:79], v[12:15], v[44:47], v[76:79]
	v_mfma_f32_16x16x32_bf16 v[80:83], v[4:7], v[52:55], v[80:83]
	v_mfma_f32_16x16x32_bf16 v[84:87], v[12:15], v[52:55], v[84:87]
	v_mfma_f32_16x16x32_bf16 v[100:103], v[12:15], v[60:63], v[88:91]
	v_mfma_f32_16x16x32_bf16 v[88:91], v[16:19], v[32:35], 0
	v_mfma_f32_16x16x32_bf16 v[32:35], v[24:27], v[32:35], 0
	v_mfma_f32_16x16x32_bf16 v[120:123], v[20:23], v[36:39], v[88:91]
	v_mfma_f32_16x16x32_bf16 v[32:35], v[28:31], v[36:39], v[32:35]
	v_mfma_f32_16x16x32_bf16 v[36:39], v[16:19], v[40:43], 0
	v_mfma_f32_16x16x32_bf16 v[40:43], v[24:27], v[40:43], 0
	v_mfma_f32_16x16x32_bf16 v[36:39], v[20:23], v[44:47], v[36:39]
	v_mfma_f32_16x16x32_bf16 v[40:43], v[28:31], v[44:47], v[40:43]
	v_mfma_f32_16x16x32_bf16 v[44:47], v[16:19], v[48:51], 0
	v_mfma_f32_16x16x32_bf16 v[48:51], v[24:27], v[48:51], 0
	v_mfma_f32_16x16x32_bf16 v[44:47], v[20:23], v[52:55], v[44:47]
	v_mfma_f32_16x16x32_bf16 v[48:51], v[28:31], v[52:55], v[48:51]
	v_mfma_f32_16x16x32_bf16 v[52:55], v[16:19], v[56:59], 0
	v_mfma_f32_16x16x32_bf16 v[56:59], v[24:27], v[56:59], 0
	v_mfma_f32_16x16x32_bf16 v[52:55], v[20:23], v[60:63], v[52:55]
	v_mfma_f32_16x16x32_bf16 v[56:59], v[28:31], v[60:63], v[56:59]
	s_barrier
	v_mov_b32_e32 v113, v185
	v_lshl_add_u64 v[244:245], s[22:23], 0, v[112:113]
	s_mov_b64 s[60:61], 0x100
	s_add_i32 s55, s55, s30
	v_lshl_add_u64 v[136:137], v[244:245], 0, s[60:61]
	s_mov_b32 m0, s55
	s_mov_b64 s[62:63], 0x40100
	s_add_i32 s56, s55, 0x2000
	ds_read_b128 v[60:63], v118 offset:16384
	ds_read_b128 v[88:91], v118 offset:17408
	ds_read_b128 v[92:95], v118 offset:18432
	ds_read_b128 v[104:107], v118 offset:19456
	ds_read_b128 v[108:111], v118 offset:20480
	ds_read_b128 v[124:127], v118 offset:21504
	ds_read_b128 v[128:131], v118 offset:22528
	ds_read_b128 v[132:135], v118 offset:23552
	global_load_lds_dwordx4 v[136:137], off
	v_lshl_add_u64 v[136:137], v[244:245], 0, s[62:63]
	s_mov_b32 m0, s56
	s_mov_b64 s[64:65], 0x80100
	s_add_i32 s57, s57, s30
	global_load_lds_dwordx4 v[136:137], off
	v_lshl_add_u64 v[136:137], v[244:245], 0, s[64:65]
	s_mov_b32 m0, s57
	s_mov_b64 s[66:67], 0xc0100
	s_add_i32 s58, s57, 0x2000
	global_load_lds_dwordx4 v[136:137], off
	v_lshl_add_u64 v[136:137], v[244:245], 0, s[66:67]
	s_mov_b32 m0, s58
	s_nop 0
	global_load_lds_dwordx4 v[136:137], off
	v_lshl_add_u64 v[136:137], v[206:207], 0, s[60:61]
	s_mov_b32 m0, s7
	s_nop 0
	global_load_lds_dwordx4 v[136:137], off
	v_lshl_add_u64 v[136:137], v[206:207], 0, s[62:63]
	s_mov_b32 m0, s31
	s_nop 0
	global_load_lds_dwordx4 v[136:137], off
	s_waitcnt vmcnt(24)
	s_waitcnt lgkmcnt(0)
	s_barrier
	s_waitcnt lgkmcnt(0)
	v_mfma_f32_16x16x32_bf16 v[136:139], v[0:3], v[60:63], 0
	v_mfma_f32_16x16x32_bf16 v[144:147], v[0:3], v[92:95], 0
	v_mfma_f32_16x16x32_bf16 v[152:155], v[0:3], v[108:111], 0
	v_mfma_f32_16x16x32_bf16 v[0:3], v[0:3], v[128:131], 0
	v_mfma_f32_16x16x32_bf16 v[136:139], v[4:7], v[88:91], v[136:139]
	v_mfma_f32_16x16x32_bf16 v[144:147], v[4:7], v[104:107], v[144:147]
	v_mfma_f32_16x16x32_bf16 v[152:155], v[4:7], v[124:127], v[152:155]
	v_mfma_f32_16x16x32_bf16 v[0:3], v[4:7], v[132:135], v[0:3]
	v_mfma_f32_16x16x32_bf16 v[4:7], v[8:11], v[128:131], 0
	v_mfma_f32_16x16x32_bf16 v[140:143], v[8:11], v[60:63], 0
	v_mfma_f32_16x16x32_bf16 v[148:151], v[8:11], v[92:95], 0
	v_mfma_f32_16x16x32_bf16 v[156:159], v[8:11], v[108:111], 0
	v_mfma_f32_16x16x32_bf16 v[4:7], v[12:15], v[132:135], v[4:7]
	v_mfma_f32_16x16x32_bf16 v[140:143], v[12:15], v[88:91], v[140:143]
	v_mfma_f32_16x16x32_bf16 v[148:151], v[12:15], v[104:107], v[148:151]
	v_mfma_f32_16x16x32_bf16 v[156:159], v[12:15], v[124:127], v[156:159]
	v_mfma_f32_16x16x32_bf16 v[8:11], v[16:19], v[60:63], 0
	v_mfma_f32_16x16x32_bf16 v[160:163], v[20:23], v[88:91], v[8:11]
	v_mfma_f32_16x16x32_bf16 v[8:11], v[24:27], v[60:63], 0
	v_mfma_f32_16x16x32_bf16 v[180:183], v[28:31], v[88:91], v[8:11]
	v_mfma_f32_16x16x32_bf16 v[8:11], v[16:19], v[92:95], 0
	v_mfma_f32_16x16x32_bf16 v[188:191], v[20:23], v[104:107], v[8:11]
	v_mfma_f32_16x16x32_bf16 v[8:11], v[24:27], v[92:95], 0
	v_mfma_f32_16x16x32_bf16 v[192:195], v[28:31], v[104:107], v[8:11]
	v_mfma_f32_16x16x32_bf16 v[8:11], v[16:19], v[108:111], 0
	v_mfma_f32_16x16x32_bf16 v[196:199], v[20:23], v[124:127], v[8:11]
	v_mfma_f32_16x16x32_bf16 v[8:11], v[24:27], v[108:111], 0
	v_mfma_f32_16x16x32_bf16 v[124:127], v[28:31], v[124:127], v[8:11]
	v_mfma_f32_16x16x32_bf16 v[8:11], v[16:19], v[128:131], 0
	v_mfma_f32_16x16x32_bf16 v[200:203], v[20:23], v[132:135], v[8:11]
	v_mfma_f32_16x16x32_bf16 v[8:11], v[24:27], v[128:131], 0
	v_mfma_f32_16x16x32_bf16 v[128:131], v[28:31], v[132:135], v[8:11]
	s_barrier
	s_add_i32 s59, 0, 0x18000
	s_add_i32 s61, 0, 0x1c000
	v_add_u32_e32 v113, s59, v119
	v_add_u32_e32 v119, s61, v119
	s_nop 0
	ds_read_b128 v[8:11], v113
	ds_read_b128 v[12:15], v113 offset:1024
	ds_read_b128 v[16:19], v113 offset:2048
	ds_read_b128 v[20:23], v113 offset:3072
	ds_read_b128 v[132:135], v119
	ds_read_b128 v[212:215], v119 offset:1024
	ds_read_b128 v[216:219], v119 offset:2048
	ds_read_b128 v[220:223], v119 offset:3072
	s_mov_b32 m0, s34
	v_lshl_add_u64 v[88:89], v[206:207], 0, s[64:65]
	ds_read_b128 v[24:27], v118 offset:32768
	ds_read_b128 v[28:31], v118 offset:33792
	ds_read_b128 v[60:63], v118 offset:34816
	ds_read_b128 v[224:227], v118 offset:35840
	ds_read_b128 v[228:231], v118 offset:36864
	ds_read_b128 v[232:235], v118 offset:37888
	ds_read_b128 v[236:239], v118 offset:38912
	ds_read_b128 v[240:243], v118 offset:39936
	global_load_lds_dwordx4 v[88:89], off
	v_lshl_add_u64 v[88:89], v[206:207], 0, s[66:67]
	s_mov_b32 m0, s35
	s_nop 0
	global_load_lds_dwordx4 v[88:89], off
	s_waitcnt vmcnt(8)
	s_waitcnt lgkmcnt(0)
	s_barrier
	s_waitcnt lgkmcnt(0)
	v_mfma_f32_16x16x32_bf16 v[64:67], v[8:11], v[24:27], v[64:67]
	v_mfma_f32_16x16x32_bf16 v[172:175], v[12:15], v[28:31], v[64:67]
	v_mfma_f32_16x16x32_bf16 v[64:67], v[16:19], v[24:27], v[68:71]
	v_mfma_f32_16x16x32_bf16 v[164:167], v[20:23], v[28:31], v[64:67]
	v_mfma_f32_16x16x32_bf16 v[64:67], v[8:11], v[60:63], v[72:75]
	v_mfma_f32_16x16x32_bf16 v[108:111], v[12:15], v[224:227], v[64:67]
	v_mfma_f32_16x16x32_bf16 v[64:67], v[16:19], v[60:63], v[76:79]
	v_mfma_f32_16x16x32_bf16 v[104:107], v[20:23], v[224:227], v[64:67]
	v_mfma_f32_16x16x32_bf16 v[64:67], v[8:11], v[228:231], v[80:83]
	v_mfma_f32_16x16x32_bf16 v[92:95], v[12:15], v[232:235], v[64:67]
	v_mfma_f32_16x16x32_bf16 v[64:67], v[16:19], v[228:231], v[84:87]
	v_mfma_f32_16x16x32_bf16 v[88:91], v[20:23], v[232:235], v[64:67]
	v_mfma_f32_16x16x32_bf16 v[64:67], v[8:11], v[236:239], v[96:99]
	v_mfma_f32_16x16x32_bf16 v[76:79], v[12:15], v[240:243], v[64:67]
	v_mfma_f32_16x16x32_bf16 v[64:67], v[16:19], v[236:239], v[100:103]
	v_mfma_f32_16x16x32_bf16 v[68:71], v[20:23], v[240:243], v[64:67]
	v_mfma_f32_16x16x32_bf16 v[64:67], v[132:135], v[24:27], v[120:123]
	v_mfma_f32_16x16x32_bf16 v[24:27], v[216:219], v[24:27], v[32:35]
	v_mfma_f32_16x16x32_bf16 v[168:171], v[220:223], v[28:31], v[24:27]
	v_mfma_f32_16x16x32_bf16 v[24:27], v[132:135], v[60:63], v[36:39]
	v_mfma_f32_16x16x32_bf16 v[100:103], v[212:215], v[224:227], v[24:27]
	v_mfma_f32_16x16x32_bf16 v[24:27], v[216:219], v[60:63], v[40:43]
	v_mfma_f32_16x16x32_bf16 v[96:99], v[220:223], v[224:227], v[24:27]
	v_mfma_f32_16x16x32_bf16 v[24:27], v[132:135], v[228:231], v[44:47]
	v_mfma_f32_16x16x32_bf16 v[84:87], v[212:215], v[232:235], v[24:27]
	v_mfma_f32_16x16x32_bf16 v[24:27], v[216:219], v[228:231], v[48:51]
	v_mfma_f32_16x16x32_bf16 v[80:83], v[220:223], v[232:235], v[24:27]
	v_mfma_f32_16x16x32_bf16 v[24:27], v[132:135], v[236:239], v[52:55]
	v_mfma_f32_16x16x32_bf16 v[176:179], v[212:215], v[28:31], v[64:67]
	v_mfma_f32_16x16x32_bf16 v[64:67], v[212:215], v[240:243], v[24:27]
	v_mfma_f32_16x16x32_bf16 v[24:27], v[216:219], v[236:239], v[56:59]
	v_mfma_f32_16x16x32_bf16 v[52:55], v[220:223], v[240:243], v[24:27]
	s_barrier
; #define PG8_WAIT_V(n) asm volatile("s_waitcnt vmcnt(" #n ")" ::: "memory")
; #define PG8_WAIT_VP() asm volatile("s_waitcnt vmcnt(%0)" :: "n"(8 + Epi::NST) : "memory")
; template <class Epi, class Sched>
; __device__ __forceinline__ void gemm_phase(PG8_LAS unsigned char* lds, const Sched& S, const Epi& E, int tid_in) {
;     ...
;         { const int t = 0; PG8_KITER(PG8_WAIT_VP()); }
;         for (int t = 2; t < nt; t += 2) PG8_KITER(PG8_WAIT_V(8));
	s_mov_b64 s[64:65], 0x180
	s_add_i32 s59, s59, s30
	s_nop 2
	v_lshl_add_u64 v[24:25], v[244:245], 0, s[64:65]
	s_mov_b32 m0, s59
	s_mov_b64 s[66:67], 0x40180
	s_add_i32 s60, s59, 0x2000
	ds_read_b128 v[32:35], v118 offset:49152
	ds_read_b128 v[36:39], v118 offset:50176
	ds_read_b128 v[120:123], v118 offset:51200
	ds_read_b128 v[224:227], v118 offset:52224
	ds_read_b128 v[228:231], v118 offset:53248
	ds_read_b128 v[232:235], v118 offset:54272
	ds_read_b128 v[236:239], v118 offset:55296
	ds_read_b128 v[240:243], v118 offset:56320
	global_load_lds_dwordx4 v[24:25], off
	v_lshl_add_u64 v[24:25], v[244:245], 0, s[66:67]
	s_mov_b32 m0, s60
	s_add_i32 s61, s61, s30
	global_load_lds_dwordx4 v[24:25], off
	v_lshl_add_u64 v[24:25], v[244:245], 0, s[70:71]
	s_mov_b32 m0, s61
	s_add_i32 s62, s61, 0x2000
	global_load_lds_dwordx4 v[24:25], off
	v_lshl_add_u64 v[24:25], v[244:245], 0, s[72:73]
	s_mov_b32 m0, s62
	s_nop 0
	global_load_lds_dwordx4 v[24:25], off
	v_lshl_add_u64 v[24:25], v[206:207], 0, s[64:65]
	s_mov_b32 m0, s44
	s_nop 0
	global_load_lds_dwordx4 v[24:25], off
	v_lshl_add_u64 v[24:25], v[206:207], 0, s[66:67]
	s_mov_b32 m0, s45
	s_nop 0
	global_load_lds_dwordx4 v[24:25], off
	s_waitcnt vmcnt(8)
	s_waitcnt lgkmcnt(0)
	s_barrier
	s_waitcnt lgkmcnt(0)
	v_mfma_f32_16x16x32_bf16 v[24:27], v[8:11], v[32:35], v[136:139]
	v_mfma_f32_16x16x32_bf16 v[72:75], v[12:15], v[36:39], v[24:27]
	v_mfma_f32_16x16x32_bf16 v[24:27], v[16:19], v[32:35], v[140:143]
	v_mfma_f32_16x16x32_bf16 v[60:63], v[20:23], v[36:39], v[24:27]
	v_mfma_f32_16x16x32_bf16 v[24:27], v[8:11], v[120:123], v[144:147]
	v_mfma_f32_16x16x32_bf16 v[44:47], v[12:15], v[224:227], v[24:27]
	v_mfma_f32_16x16x32_bf16 v[24:27], v[16:19], v[120:123], v[148:151]
	v_mfma_f32_16x16x32_bf16 v[40:43], v[20:23], v[224:227], v[24:27]
	v_mfma_f32_16x16x32_bf16 v[24:27], v[8:11], v[228:231], v[152:155]
	v_mfma_f32_16x16x32_bf16 v[0:3], v[8:11], v[236:239], v[0:3]
	v_mfma_f32_16x16x32_bf16 v[28:31], v[12:15], v[232:235], v[24:27]
	v_mfma_f32_16x16x32_bf16 v[24:27], v[16:19], v[228:231], v[156:159]
	v_mfma_f32_16x16x32_bf16 v[12:15], v[12:15], v[240:243], v[0:3]
	v_mfma_f32_16x16x32_bf16 v[0:3], v[16:19], v[236:239], v[4:7]
	v_mfma_f32_16x16x32_bf16 v[24:27], v[20:23], v[232:235], v[24:27]
	v_mfma_f32_16x16x32_bf16 v[8:11], v[20:23], v[240:243], v[0:3]
	v_mfma_f32_16x16x32_bf16 v[0:3], v[132:135], v[32:35], v[160:163]
	v_mfma_f32_16x16x32_bf16 v[56:59], v[212:215], v[36:39], v[0:3]
	v_mfma_f32_16x16x32_bf16 v[0:3], v[216:219], v[32:35], v[180:183]
	v_mfma_f32_16x16x32_bf16 v[48:51], v[220:223], v[36:39], v[0:3]
	v_mfma_f32_16x16x32_bf16 v[0:3], v[132:135], v[120:123], v[188:191]
	v_mfma_f32_16x16x32_bf16 v[36:39], v[212:215], v[224:227], v[0:3]
	v_mfma_f32_16x16x32_bf16 v[0:3], v[216:219], v[120:123], v[192:195]
	v_mfma_f32_16x16x32_bf16 v[32:35], v[220:223], v[224:227], v[0:3]
	v_mfma_f32_16x16x32_bf16 v[0:3], v[132:135], v[228:231], v[196:199]
	v_mfma_f32_16x16x32_bf16 v[20:23], v[212:215], v[232:235], v[0:3]
	v_mfma_f32_16x16x32_bf16 v[0:3], v[216:219], v[228:231], v[124:127]
	v_mfma_f32_16x16x32_bf16 v[16:19], v[220:223], v[232:235], v[0:3]
	v_mfma_f32_16x16x32_bf16 v[0:3], v[132:135], v[236:239], v[200:203]
	v_mfma_f32_16x16x32_bf16 v[4:7], v[212:215], v[240:243], v[0:3]
	v_mfma_f32_16x16x32_bf16 v[0:3], v[216:219], v[236:239], v[128:131]
	v_mfma_f32_16x16x32_bf16 v[0:3], v[220:223], v[240:243], v[0:3]
	s_barrier
	s_add_u32 s20, s20, 0x80180
	s_addc_u32 s21, s21, 0
	s_add_u32 s63, s22, 0x200
	s_addc_u32 s64, s23, 0
	s_mov_b32 s65, 0
